# gating epilogues of GEMM2/GEMM3: bias add and -log2e scale fused into one FMA (bias pre-scaled once per tile), 128 fewer VALU ops per wave per tile
# speedup vs baseline: 1.0003x; 1.0003x over previous
; #define GAS __attribute__((address_space(1)))
; __device__ __forceinline__ void unpack8(const v4u v, float (&f)[8]) { f[0] = bflo(v.x); f[1] = bfhi(v.x); f[2] = bflo(v.y); f[3] = bfhi(v.y); f[4] = bflo(v.z); f[5] = bfhi(v.z); f[6] = bflo(v.w); f[7] = bfhi(v.w); }
; __device__ __forceinline__ v4u pack8(const float (&f)[8]) { v4u o; o.x = cvt_pk_bf16(f[0], f[1]); o.y = cvt_pk_bf16(f[2], f[3]); o.z = cvt_pk_bf16(f[4], f[5]); o.w = cvt_pk_bf16(f[6], f[7]); return o; }
; __device__ __forceinline__ float sigmoidf_(float x) { return __builtin_amdgcn_rcpf(1.f + __expf(-x)); }
;     __device__ __forceinline__ void operator()(const f32x4 (&acc)[2][2][4][2], const pg8::Unit& u, int wr, int wc, int fr, int fq) const {
;     ...
;         for (int bj = 0; bj < 2; ++bj) { const int col = col0 + bj * 128;
;             const f32x4 b0 = *(const GAS f32x4*)(bgate + WHICH * DM + col), b1 = *(const GAS f32x4*)(bgate + WHICH * DM + col + 4);
; #pragma unroll
;             for (int aim = 0; aim < 4; ++aim) { const int ai = aim >> 1, mb = (aim & 1) * 2;
;                 v4u gv[4], tv[4];
; #pragma unroll
;                 for (int m = mb; m < mb + 2; ++m) { const int row = row0 + ai * 128 + m * 16;
;                     gv[m] = __builtin_nontemporal_load((const GAS v4u*)(proj + (size_t)row * NPROJ + OFF_GATE + WHICH * DM + col));
;                     if (WHICH == 1) tv[m] = *(const GAS v4u*)(ta + (size_t)row * DM + col); }
; #pragma unroll
;                 for (int m = mb; m < mb + 2; ++m) { const int row = row0 + ai * 128 + m * 16; float g[8]; unpack8(gv[m], g);
;                     const f32x4 a0 = acc[ai][bj][m][0], a1 = acc[ai][bj][m][1]; float r[8];
; #pragma unroll
;                     for (int e = 0; e < 4; ++e) { r[e] = sigmoidf_(g[e] + b0[e]) * a0[e]; r[4 + e] = sigmoidf_(g[4 + e] + b1[e]) * a1[e]; }
;                     if (WHICH == 0) *(GAS v4u*)(ta + (size_t)row * DM + col) = pack8(r);
;                     else { float tf[8]; unpack8(tv[m], tf);
; #pragma unroll
;                         for (int e = 0; e < 8; ++e) r[e] += tf[e];
;                         *(GAS v4u*)(mix + (size_t)row * DM + col) = pack8(r); } }
.LBB0_410:
	v_lshl_add_u32 v164, s22, 8, v170
	v_lshl_or_b32 v154, s9, 8, v179
	v_mov_b64_e32 v[166:167], s[42:43]
	v_ashrrev_i32_e32 v155, 31, v154
	v_readlane_b32 s60, v252, 8
	v_mad_i64_i32 v[140:141], s[0:1], v164, s4, v[166:167]
	s_mov_b64 s[14:15], 0x8000
	v_readlane_b32 s68, v252, 16
	v_readlane_b32 s69, v252, 17
	v_lshl_add_u64 v[160:161], v[140:141], 0, s[14:15]
	v_lshlrev_b64 v[162:163], 1, v[154:155]
	v_lshl_add_u64 v[156:157], v[154:155], 2, s[68:69]
	v_lshl_add_u64 v[140:141], v[160:161], 0, v[162:163]
	global_load_dwordx4 v[100:103], v[156:157], off offset:16
	global_load_dwordx4 v[104:107], v[156:157], off
	global_load_dwordx4 v[186:189], v[140:141], off nt
	v_or_b32_e32 v168, 16, v164
	v_mad_i64_i32 v[140:141], s[0:1], v168, s4, v[166:167]
	v_lshl_add_u64 v[158:159], v[140:141], 0, s[14:15]
	v_lshl_add_u64 v[140:141], v[158:159], 0, v[162:163]
	global_load_dwordx4 v[140:143], v[140:141], off nt
	v_ashrrev_i32_e32 v165, 31, v164
	v_ashrrev_i32_e32 v169, 31, v168
	s_andn2_b64 vcc, exec, s[40:41]
	v_readlane_b32 s61, v252, 9
	v_readlane_b32 s62, v252, 10
	v_readlane_b32 s63, v252, 11
	v_readlane_b32 s64, v252, 12
	v_readlane_b32 s65, v252, 13
	v_readlane_b32 s66, v252, 14
	v_readlane_b32 s67, v252, 15
	v_readlane_b32 s70, v252, 18
	v_readlane_b32 s71, v252, 19
	v_readlane_b32 s72, v252, 20
	v_readlane_b32 s73, v252, 21
	v_readlane_b32 s74, v252, 22
	v_readlane_b32 s75, v252, 23
	s_waitcnt vmcnt(0)
	v_lshlrev_b32_e32 v155, 16, v186
	v_mul_f32_e32 v104, 0xbfb8aa3b, v104
	v_fmamk_f32 v155, v155, 0xbfb8aa3b, v104
	v_exp_f32_e32 v155, v155
	v_lshlrev_b32_e32 v190, 16, v188
	v_and_b32_e32 v185, 0xffff0000, v186
	v_and_b32_e32 v188, 0xffff0000, v188
	v_add_f32_e32 v155, 1.0, v155
	v_rcp_f32_e32 v155, v155
	v_lshlrev_b32_e32 v186, 16, v187
	v_lshlrev_b32_e32 v191, 16, v189
	v_and_b32_e32 v187, 0xffff0000, v187
	v_mul_f32_e32 v136, v136, v155
	v_mul_f32_e32 v100, 0xbfb8aa3b, v100
	v_fmamk_f32 v155, v190, 0xbfb8aa3b, v100
	v_exp_f32_e32 v155, v155
	v_and_b32_e32 v189, 0xffff0000, v189
	v_add_f32_e32 v155, 1.0, v155
	v_rcp_f32_e32 v155, v155
	s_nop 0
	v_mul_f32_e32 v155, v132, v155
	v_mul_f32_e32 v105, 0xbfb8aa3b, v105
	v_fmamk_f32 v132, v185, 0xbfb8aa3b, v105
	v_exp_f32_e32 v132, v132
	s_nop 0
	v_add_f32_e32 v132, 1.0, v132
	v_rcp_f32_e32 v132, v132
	s_nop 0
	v_mul_f32_e32 v132, v137, v132
	v_mul_f32_e32 v101, 0xbfb8aa3b, v101
	v_fmamk_f32 v137, v188, 0xbfb8aa3b, v101
	v_exp_f32_e32 v137, v137
	v_cvt_pk_bf16_f32 v132, v136, v132
	s_nop 0
	v_add_f32_e32 v137, 1.0, v137
	v_rcp_f32_e32 v137, v137
	s_nop 0
	v_mul_f32_e32 v137, v133, v137
	v_mul_f32_e32 v106, 0xbfb8aa3b, v106
	v_fmamk_f32 v133, v186, 0xbfb8aa3b, v106
	v_exp_f32_e32 v133, v133
	s_nop 0
	v_add_f32_e32 v133, 1.0, v133
	v_rcp_f32_e32 v133, v133
	s_nop 0
	v_mul_f32_e32 v133, v138, v133
	v_mul_f32_e32 v102, 0xbfb8aa3b, v102
	v_fmamk_f32 v138, v191, 0xbfb8aa3b, v102
	v_exp_f32_e32 v138, v138
	s_nop 0
	v_add_f32_e32 v138, 1.0, v138
	v_rcp_f32_e32 v138, v138
	s_nop 0
	v_mul_f32_e32 v138, v134, v138
	v_mul_f32_e32 v107, 0xbfb8aa3b, v107
	v_fmamk_f32 v134, v187, 0xbfb8aa3b, v107
	v_exp_f32_e32 v134, v134
	s_nop 0
	v_add_f32_e32 v134, 1.0, v134
	v_rcp_f32_e32 v134, v134
	s_nop 0
	v_mul_f32_e32 v134, v139, v134
	v_mul_f32_e32 v103, 0xbfb8aa3b, v103
	v_fmamk_f32 v139, v189, 0xbfb8aa3b, v103
	v_exp_f32_e32 v139, v139
	v_cvt_pk_bf16_f32 v133, v133, v134
	v_cvt_pk_bf16_f32 v134, v155, v137
	v_lshlrev_b64 v[136:137], 12, v[164:165]
	v_add_f32_e32 v139, 1.0, v139
	v_rcp_f32_e32 v139, v139
	v_lshl_add_u64 v[136:137], s[44:45], 0, v[136:137]
	v_lshl_add_u64 v[136:137], v[136:137], 0, v[162:163]
	v_mul_f32_e32 v135, v135, v139
	v_cvt_pk_bf16_f32 v135, v138, v135
	global_store_dwordx4 v[136:137], v[132:135], off
	v_lshlrev_b32_e32 v138, 16, v142
	v_and_b32_e32 v139, 0xffff0000, v142
	v_lshlrev_b32_e32 v132, 16, v140
	v_fmamk_f32 v132, v132, 0xbfb8aa3b, v104
	v_exp_f32_e32 v132, v132
	v_and_b32_e32 v133, 0xffff0000, v140
	v_lshlrev_b32_e32 v134, 16, v141
	v_lshlrev_b32_e32 v140, 16, v143
	v_add_f32_e32 v132, 1.0, v132
	v_rcp_f32_e32 v132, v132
	v_and_b32_e32 v135, 0xffff0000, v141
	v_and_b32_e32 v141, 0xffff0000, v143
	v_mul_f32_e32 v128, v128, v132
	v_fmamk_f32 v132, v138, 0xbfb8aa3b, v100
	v_exp_f32_e32 v132, v132
	v_or_b32_e32 v138, 32, v164
	v_add_f32_e32 v132, 1.0, v132
	v_rcp_f32_e32 v132, v132
	s_nop 0
	v_mul_f32_e32 v132, v124, v132
	v_fmamk_f32 v124, v133, 0xbfb8aa3b, v105
	v_exp_f32_e32 v124, v124
	s_nop 0
	v_add_f32_e32 v124, 1.0, v124
	v_rcp_f32_e32 v124, v124
	s_nop 0
	v_mul_f32_e32 v124, v129, v124
	v_fmamk_f32 v129, v139, 0xbfb8aa3b, v101
	v_exp_f32_e32 v129, v129
	v_cvt_pk_bf16_f32 v124, v128, v124
	v_ashrrev_i32_e32 v139, 31, v138
	v_add_f32_e32 v129, 1.0, v129
	v_rcp_f32_e32 v129, v129
	s_nop 0
	v_mul_f32_e32 v129, v125, v129
	v_fmamk_f32 v125, v134, 0xbfb8aa3b, v106
	v_exp_f32_e32 v125, v125
	v_or_b32_e32 v134, 48, v164
	v_add_f32_e32 v125, 1.0, v125
	v_rcp_f32_e32 v125, v125
	s_nop 0
	v_mul_f32_e32 v125, v130, v125
	v_fmamk_f32 v130, v140, 0xbfb8aa3b, v102
	v_exp_f32_e32 v130, v130
	s_nop 0
	v_add_f32_e32 v130, 1.0, v130
	v_rcp_f32_e32 v130, v130
	s_nop 0
	v_mul_f32_e32 v130, v126, v130
	v_fmamk_f32 v126, v135, 0xbfb8aa3b, v107
	v_exp_f32_e32 v126, v126
	v_ashrrev_i32_e32 v135, 31, v134
	v_add_f32_e32 v126, 1.0, v126
	v_rcp_f32_e32 v126, v126
	s_nop 0
	v_mul_f32_e32 v126, v131, v126
	v_fmamk_f32 v131, v141, 0xbfb8aa3b, v103
	v_exp_f32_e32 v131, v131
	v_cvt_pk_bf16_f32 v125, v125, v126
	v_cvt_pk_bf16_f32 v126, v132, v129
	v_lshlrev_b64 v[128:129], 12, v[168:169]
	v_add_f32_e32 v131, 1.0, v131
	v_rcp_f32_e32 v131, v131
	v_lshl_add_u64 v[128:129], s[44:45], 0, v[128:129]
	v_lshl_add_u64 v[128:129], v[128:129], 0, v[162:163]
	v_mul_f32_e32 v127, v127, v131
	v_cvt_pk_bf16_f32 v127, v130, v127
	global_store_dwordx4 v[128:129], v[124:127], off
	s_nop 1
	v_mad_i64_i32 v[124:125], s[0:1], v138, s4, v[166:167]
	v_lshl_add_u64 v[130:131], v[124:125], 0, s[14:15]
	v_lshl_add_u64 v[124:125], v[130:131], 0, v[162:163]
	global_load_dwordx4 v[140:143], v[124:125], off nt
	v_mad_i64_i32 v[124:125], s[0:1], v134, s4, v[166:167]
	v_lshl_add_u64 v[132:133], v[124:125], 0, s[14:15]
	v_lshl_add_u64 v[124:125], v[132:133], 0, v[162:163]
	global_load_dwordx4 v[124:127], v[124:125], off nt
	s_waitcnt vmcnt(1)
; #define GAS __attribute__((address_space(1)))
; __device__ __forceinline__ void unpack8(const v4u v, float (&f)[8]) { f[0] = bflo(v.x); f[1] = bfhi(v.x); f[2] = bflo(v.y); f[3] = bfhi(v.y); f[4] = bflo(v.z); f[5] = bfhi(v.z); f[6] = bflo(v.w); f[7] = bfhi(v.w); }
; __device__ __forceinline__ v4u pack8(const float (&f)[8]) { v4u o; o.x = cvt_pk_bf16(f[0], f[1]); o.y = cvt_pk_bf16(f[2], f[3]); o.z = cvt_pk_bf16(f[4], f[5]); o.w = cvt_pk_bf16(f[6], f[7]); return o; }
; __device__ __forceinline__ float sigmoidf_(float x) { return __builtin_amdgcn_rcpf(1.f + __expf(-x)); }
;     __device__ __forceinline__ void operator()(const f32x4 (&acc)[2][2][4][2], const pg8::Unit& u, int wr, int wc, int fr, int fq) const {
;     ...
;             for (int aim = 0; aim < 4; ++aim) { const int ai = aim >> 1, mb = (aim & 1) * 2;
;                 v4u gv[4], tv[4];
; #pragma unroll
;                 for (int m = mb; m < mb + 2; ++m) { const int row = row0 + ai * 128 + m * 16;
;                     gv[m] = __builtin_nontemporal_load((const GAS v4u*)(proj + (size_t)row * NPROJ + OFF_GATE + WHICH * DM + col));
;                     if (WHICH == 1) tv[m] = *(const GAS v4u*)(ta + (size_t)row * DM + col); }
; #pragma unroll
;                 for (int m = mb; m < mb + 2; ++m) { const int row = row0 + ai * 128 + m * 16; float g[8]; unpack8(gv[m], g);
;                     const f32x4 a0 = acc[ai][bj][m][0], a1 = acc[ai][bj][m][1]; float r[8];
; #pragma unroll
;                     for (int e = 0; e < 4; ++e) { r[e] = sigmoidf_(g[e] + b0[e]) * a0[e]; r[4 + e] = sigmoidf_(g[4 + e] + b1[e]) * a1[e]; }
;                     if (WHICH == 0) *(GAS v4u*)(ta + (size_t)row * DM + col) = pack8(r);
;                     else { float tf[8]; unpack8(tv[m], tf);
; #pragma unroll
;                         for (int e = 0; e < 8; ++e) r[e] += tf[e];
;                         *(GAS v4u*)(mix + (size_t)row * DM + col) = pack8(r); } }
	v_lshlrev_b32_e32 v155, 16, v140
	v_and_b32_e32 v140, 0xffff0000, v140
	v_fmamk_f32 v140, v140, 0xbfb8aa3b, v105
	v_exp_f32_e32 v140, v140
	v_lshlrev_b32_e32 v168, 16, v142
	v_and_b32_e32 v142, 0xffff0000, v142
	v_lshlrev_b32_e32 v165, 16, v141
	v_add_f32_e32 v140, 1.0, v140
	v_rcp_f32_e32 v140, v140
	v_lshlrev_b32_e32 v169, 16, v143
	v_and_b32_e32 v141, 0xffff0000, v141
	v_fmamk_f32 v155, v155, 0xbfb8aa3b, v104
	v_mul_f32_e32 v121, v121, v140
	v_fmamk_f32 v140, v142, 0xbfb8aa3b, v101
	v_exp_f32_e32 v140, v140
	v_exp_f32_e32 v155, v155
	v_and_b32_e32 v143, 0xffff0000, v143
	v_add_f32_e32 v140, 1.0, v140
	v_rcp_f32_e32 v140, v140
	v_add_f32_e32 v155, 1.0, v155
	v_rcp_f32_e32 v155, v155
	v_mul_f32_e32 v117, v117, v140
	v_fmamk_f32 v140, v165, 0xbfb8aa3b, v106
	v_exp_f32_e32 v140, v140
	v_mul_f32_e32 v120, v120, v155
	v_fmamk_f32 v155, v168, 0xbfb8aa3b, v100
	v_add_f32_e32 v140, 1.0, v140
	v_rcp_f32_e32 v140, v140
	v_exp_f32_e32 v155, v155
	v_mul_f32_e32 v122, v122, v140
	v_fmamk_f32 v140, v169, 0xbfb8aa3b, v102
	v_exp_f32_e32 v140, v140
	v_add_f32_e32 v155, 1.0, v155
	v_rcp_f32_e32 v155, v155
	v_add_f32_e32 v140, 1.0, v140
	v_rcp_f32_e32 v140, v140
	v_mul_f32_e32 v116, v116, v155
	v_mul_f32_e32 v140, v118, v140
	v_fmamk_f32 v118, v141, 0xbfb8aa3b, v107
	v_exp_f32_e32 v118, v118
	s_nop 0
	v_add_f32_e32 v118, 1.0, v118
	v_rcp_f32_e32 v118, v118
	s_nop 0
	v_mul_f32_e32 v123, v123, v118
	v_fmamk_f32 v118, v143, 0xbfb8aa3b, v103
	v_exp_f32_e32 v118, v118
	s_nop 0
	v_add_f32_e32 v118, 1.0, v118
	v_rcp_f32_e32 v118, v118
	s_nop 0
	v_mul_f32_e32 v141, v119, v118
	v_cvt_pk_bf16_f32 v118, v120, v121
	v_cvt_pk_bf16_f32 v119, v122, v123
	v_cvt_pk_bf16_f32 v120, v116, v117
	v_lshlrev_b64 v[116:117], 12, v[138:139]
	v_lshl_add_u64 v[116:117], s[44:45], 0, v[116:117]
	v_lshl_add_u64 v[116:117], v[116:117], 0, v[162:163]
	v_cvt_pk_bf16_f32 v121, v140, v141
	global_store_dwordx4 v[116:117], v[118:121], off
	s_waitcnt vmcnt(1)
	v_lshlrev_b32_e32 v122, 16, v126
	v_and_b32_e32 v123, 0xffff0000, v126
	v_lshlrev_b32_e32 v118, 16, v124
	v_fmamk_f32 v118, v118, 0xbfb8aa3b, v104
	v_exp_f32_e32 v118, v118
	v_and_b32_e32 v119, 0xffff0000, v124
	v_lshlrev_b32_e32 v120, 16, v125
	v_lshlrev_b32_e32 v124, 16, v127
	v_add_f32_e32 v118, 1.0, v118
	v_rcp_f32_e32 v118, v118
	v_and_b32_e32 v121, 0xffff0000, v125
	v_and_b32_e32 v125, 0xffff0000, v127
	v_add_u32_e32 v126, 0x80, v164
	v_mul_f32_e32 v112, v112, v118
	v_fmamk_f32 v118, v122, 0xbfb8aa3b, v100
	v_exp_f32_e32 v118, v118
	v_ashrrev_i32_e32 v127, 31, v126
	v_add_f32_e32 v118, 1.0, v118
	v_rcp_f32_e32 v118, v118
	s_nop 0
	v_mul_f32_e32 v108, v108, v118
	v_fmamk_f32 v118, v119, 0xbfb8aa3b, v105
	v_exp_f32_e32 v118, v118
	s_nop 0
	v_add_f32_e32 v118, 1.0, v118
	v_rcp_f32_e32 v118, v118
	s_nop 0
	v_mul_f32_e32 v113, v113, v118
	v_fmamk_f32 v118, v123, 0xbfb8aa3b, v101
	v_exp_f32_e32 v118, v118
	s_nop 0
	v_add_f32_e32 v118, 1.0, v118
	v_rcp_f32_e32 v118, v118
	s_nop 0
	v_mul_f32_e32 v109, v109, v118
	v_fmamk_f32 v118, v120, 0xbfb8aa3b, v106
	v_exp_f32_e32 v118, v118
	s_nop 0
	v_add_f32_e32 v118, 1.0, v118
	v_rcp_f32_e32 v118, v118
	s_nop 0
	v_mul_f32_e32 v114, v114, v118
	v_fmamk_f32 v118, v124, 0xbfb8aa3b, v102
	v_exp_f32_e32 v118, v118
	s_nop 0
	v_add_f32_e32 v118, 1.0, v118
	v_rcp_f32_e32 v118, v118
	s_nop 0
	v_mul_f32_e32 v118, v110, v118
	v_fmamk_f32 v110, v121, 0xbfb8aa3b, v107
	v_exp_f32_e32 v110, v110
	s_nop 0
	v_add_f32_e32 v110, 1.0, v110
	v_rcp_f32_e32 v110, v110
	s_nop 0
	v_mul_f32_e32 v115, v115, v110
	v_fmamk_f32 v110, v125, 0xbfb8aa3b, v103
	v_exp_f32_e32 v110, v110
	s_nop 0
	v_add_f32_e32 v110, 1.0, v110
	v_rcp_f32_e32 v110, v110
	s_nop 0
	v_mul_f32_e32 v119, v111, v110
	v_cvt_pk_bf16_f32 v110, v112, v113
	v_cvt_pk_bf16_f32 v111, v114, v115
	v_cvt_pk_bf16_f32 v112, v108, v109
	v_lshlrev_b64 v[108:109], 12, v[134:135]
	v_lshl_add_u64 v[108:109], s[44:45], 0, v[108:109]
	v_lshl_add_u64 v[108:109], v[108:109], 0, v[162:163]
	v_cvt_pk_bf16_f32 v113, v118, v119
	global_store_dwordx4 v[108:109], v[110:113], off
	v_add_u32_e32 v114, 0x90, v164
	v_ashrrev_i32_e32 v115, 31, v114
	v_mad_i64_i32 v[110:111], s[0:1], v126, s4, v[166:167]
	v_lshl_add_u64 v[110:111], v[110:111], 0, s[14:15]
	v_lshl_add_u64 v[112:113], v[110:111], 0, v[162:163]
	global_load_dwordx4 v[118:121], v[112:113], off nt
	v_mad_i64_i32 v[112:113], s[0:1], v114, s4, v[166:167]
	v_lshl_add_u64 v[112:113], v[112:113], 0, s[14:15]
	v_lshl_add_u64 v[122:123], v[112:113], 0, v[162:163]
	global_load_dwordx4 v[122:125], v[122:123], off nt
	s_waitcnt vmcnt(1)
	v_lshlrev_b32_e32 v134, 16, v118
	v_and_b32_e32 v118, 0xffff0000, v118
	v_fmamk_f32 v118, v118, 0xbfb8aa3b, v105
	v_exp_f32_e32 v118, v118
	v_lshlrev_b32_e32 v138, 16, v120
	v_and_b32_e32 v120, 0xffff0000, v120
	v_lshlrev_b32_e32 v135, 16, v119
	v_add_f32_e32 v118, 1.0, v118
	v_rcp_f32_e32 v118, v118
	v_lshlrev_b32_e32 v139, 16, v121
	v_and_b32_e32 v119, 0xffff0000, v119
	v_fmamk_f32 v134, v134, 0xbfb8aa3b, v104
	v_mul_f32_e32 v97, v97, v118
	v_fmamk_f32 v118, v120, 0xbfb8aa3b, v101
	v_exp_f32_e32 v118, v118
	v_exp_f32_e32 v134, v134
	v_and_b32_e32 v121, 0xffff0000, v121
	v_add_f32_e32 v118, 1.0, v118
	v_rcp_f32_e32 v118, v118
	v_add_f32_e32 v134, 1.0, v134
	v_rcp_f32_e32 v134, v134
	v_mul_f32_e32 v93, v93, v118
	v_fmamk_f32 v118, v135, 0xbfb8aa3b, v106
	v_exp_f32_e32 v118, v118
	v_mul_f32_e32 v96, v96, v134
	v_fmamk_f32 v134, v138, 0xbfb8aa3b, v100
	v_add_f32_e32 v118, 1.0, v118
	v_rcp_f32_e32 v118, v118
	v_exp_f32_e32 v134, v134
	v_mul_f32_e32 v98, v98, v118
	v_fmamk_f32 v118, v139, 0xbfb8aa3b, v102
	v_exp_f32_e32 v118, v118
	v_add_f32_e32 v134, 1.0, v134
	v_rcp_f32_e32 v134, v134
	v_add_f32_e32 v118, 1.0, v118
	v_rcp_f32_e32 v118, v118
	v_mul_f32_e32 v92, v92, v134
	v_mul_f32_e32 v118, v94, v118
	v_fmamk_f32 v94, v119, 0xbfb8aa3b, v107
	v_exp_f32_e32 v94, v94
	s_nop 0
	v_add_f32_e32 v94, 1.0, v94
	v_rcp_f32_e32 v94, v94
	s_nop 0
	v_mul_f32_e32 v99, v99, v94
	v_fmamk_f32 v94, v121, 0xbfb8aa3b, v103
	v_exp_f32_e32 v94, v94
	s_nop 0
	v_add_f32_e32 v94, 1.0, v94
	v_rcp_f32_e32 v94, v94
	s_nop 0
	v_mul_f32_e32 v119, v95, v94
	v_cvt_pk_bf16_f32 v94, v96, v97
	v_cvt_pk_bf16_f32 v95, v98, v99
	v_cvt_pk_bf16_f32 v96, v92, v93
	v_lshlrev_b64 v[92:93], 12, v[126:127]
	v_lshl_add_u64 v[92:93], s[44:45], 0, v[92:93]
	v_lshl_add_u64 v[92:93], v[92:93], 0, v[162:163]
	v_cvt_pk_bf16_f32 v97, v118, v119
	global_store_dwordx4 v[92:93], v[94:97], off
	s_waitcnt vmcnt(1)
; #define GAS __attribute__((address_space(1)))
; __device__ __forceinline__ void unpack8(const v4u v, float (&f)[8]) { f[0] = bflo(v.x); f[1] = bfhi(v.x); f[2] = bflo(v.y); f[3] = bfhi(v.y); f[4] = bflo(v.z); f[5] = bfhi(v.z); f[6] = bflo(v.w); f[7] = bfhi(v.w); }
; __device__ __forceinline__ v4u pack8(const float (&f)[8]) { v4u o; o.x = cvt_pk_bf16(f[0], f[1]); o.y = cvt_pk_bf16(f[2], f[3]); o.z = cvt_pk_bf16(f[4], f[5]); o.w = cvt_pk_bf16(f[6], f[7]); return o; }
; __device__ __forceinline__ float sigmoidf_(float x) { return __builtin_amdgcn_rcpf(1.f + __expf(-x)); }
;     __device__ __forceinline__ void operator()(const f32x4 (&acc)[2][2][4][2], const pg8::Unit& u, int wr, int wc, int fr, int fq) const {
;     ...
;         for (int bj = 0; bj < 2; ++bj) { const int col = col0 + bj * 128;
;             const f32x4 b0 = *(const GAS f32x4*)(bgate + WHICH * DM + col), b1 = *(const GAS f32x4*)(bgate + WHICH * DM + col + 4);
; #pragma unroll
;             for (int aim = 0; aim < 4; ++aim) { const int ai = aim >> 1, mb = (aim & 1) * 2;
;                 v4u gv[4], tv[4];
; #pragma unroll
;                 for (int m = mb; m < mb + 2; ++m) { const int row = row0 + ai * 128 + m * 16;
;                     gv[m] = __builtin_nontemporal_load((const GAS v4u*)(proj + (size_t)row * NPROJ + OFF_GATE + WHICH * DM + col));
;                     if (WHICH == 1) tv[m] = *(const GAS v4u*)(ta + (size_t)row * DM + col); }
; #pragma unroll
;                 for (int m = mb; m < mb + 2; ++m) { const int row = row0 + ai * 128 + m * 16; float g[8]; unpack8(gv[m], g);
;                     const f32x4 a0 = acc[ai][bj][m][0], a1 = acc[ai][bj][m][1]; float r[8];
; #pragma unroll
;                     for (int e = 0; e < 4; ++e) { r[e] = sigmoidf_(g[e] + b0[e]) * a0[e]; r[4 + e] = sigmoidf_(g[4 + e] + b1[e]) * a1[e]; }
;                     if (WHICH == 0) *(GAS v4u*)(ta + (size_t)row * DM + col) = pack8(r);
;                     else { float tf[8]; unpack8(tv[m], tf);
; #pragma unroll
;                         for (int e = 0; e < 8; ++e) r[e] += tf[e];
;                         *(GAS v4u*)(mix + (size_t)row * DM + col) = pack8(r); } }
	v_lshlrev_b32_e32 v98, 16, v124
	v_and_b32_e32 v99, 0xffff0000, v124
	v_lshlrev_b32_e32 v94, 16, v122
	v_fmamk_f32 v94, v94, 0xbfb8aa3b, v104
	v_exp_f32_e32 v94, v94
	v_and_b32_e32 v95, 0xffff0000, v122
	v_lshlrev_b32_e32 v96, 16, v123
	v_lshlrev_b32_e32 v118, 16, v125
	v_add_f32_e32 v94, 1.0, v94
	v_rcp_f32_e32 v94, v94
	v_and_b32_e32 v97, 0xffff0000, v123
	v_and_b32_e32 v119, 0xffff0000, v125
	v_mul_f32_e32 v88, v88, v94
	v_fmamk_f32 v94, v98, 0xbfb8aa3b, v100
	v_exp_f32_e32 v94, v94
	v_add_u32_e32 v98, 0xa0, v164
	v_add_f32_e32 v94, 1.0, v94
	v_rcp_f32_e32 v94, v94
	s_nop 0
	v_mul_f32_e32 v84, v84, v94
	v_fmamk_f32 v94, v95, 0xbfb8aa3b, v105
	v_exp_f32_e32 v94, v94
	s_nop 0
	v_add_f32_e32 v94, 1.0, v94
	v_rcp_f32_e32 v94, v94
	s_nop 0
	v_mul_f32_e32 v89, v89, v94
	v_fmamk_f32 v94, v99, 0xbfb8aa3b, v101
	v_exp_f32_e32 v94, v94
	v_ashrrev_i32_e32 v99, 31, v98
	v_add_f32_e32 v94, 1.0, v94
	v_rcp_f32_e32 v94, v94
	s_nop 0
	v_mul_f32_e32 v85, v85, v94
	v_fmamk_f32 v94, v96, 0xbfb8aa3b, v106
	v_exp_f32_e32 v94, v94
	s_nop 0
	v_add_f32_e32 v94, 1.0, v94
	v_rcp_f32_e32 v94, v94
	s_nop 0
	v_mul_f32_e32 v90, v90, v94
	v_fmamk_f32 v94, v118, 0xbfb8aa3b, v102
	v_exp_f32_e32 v94, v94
	s_nop 0
	v_add_f32_e32 v94, 1.0, v94
	v_rcp_f32_e32 v94, v94
	s_nop 0
	v_mul_f32_e32 v94, v86, v94
	v_fmamk_f32 v86, v97, 0xbfb8aa3b, v107
	v_exp_f32_e32 v86, v86
	s_nop 0
	v_add_f32_e32 v86, 1.0, v86
	v_rcp_f32_e32 v86, v86
	s_nop 0
	v_mul_f32_e32 v91, v91, v86
	v_fmamk_f32 v86, v119, 0xbfb8aa3b, v103
	v_exp_f32_e32 v86, v86
	s_nop 0
	v_add_f32_e32 v86, 1.0, v86
	v_rcp_f32_e32 v86, v86
	s_nop 0
	v_mul_f32_e32 v95, v87, v86
	v_cvt_pk_bf16_f32 v86, v88, v89
	v_cvt_pk_bf16_f32 v87, v90, v91
	v_cvt_pk_bf16_f32 v88, v84, v85
	v_lshlrev_b64 v[84:85], 12, v[114:115]
	v_lshl_add_u64 v[84:85], s[44:45], 0, v[84:85]
	v_lshl_add_u64 v[84:85], v[84:85], 0, v[162:163]
	v_cvt_pk_bf16_f32 v89, v94, v95
	global_store_dwordx4 v[84:85], v[86:89], off
	v_add_u32_e32 v90, 0xb0, v164
	v_ashrrev_i32_e32 v91, 31, v90
	v_mad_i64_i32 v[86:87], s[0:1], v98, s4, v[166:167]
	v_lshl_add_u64 v[86:87], v[86:87], 0, s[14:15]
	v_lshl_add_u64 v[88:89], v[86:87], 0, v[162:163]
	global_load_dwordx4 v[94:97], v[88:89], off nt
	v_mad_i64_i32 v[88:89], s[0:1], v90, s4, v[166:167]
	v_lshl_add_u64 v[88:89], v[88:89], 0, s[14:15]
	v_lshl_add_u64 v[114:115], v[88:89], 0, v[162:163]
	global_load_dwordx4 v[118:121], v[114:115], off nt
	s_mov_b64 s[0:1], -1
	s_waitcnt vmcnt(1)
	v_lshlrev_b32_e32 v114, 16, v94
	v_and_b32_e32 v94, 0xffff0000, v94
	v_fmamk_f32 v94, v94, 0xbfb8aa3b, v105
	v_exp_f32_e32 v94, v94
	v_lshlrev_b32_e32 v122, 16, v96
	v_and_b32_e32 v96, 0xffff0000, v96
	v_lshlrev_b32_e32 v115, 16, v95
	v_add_f32_e32 v94, 1.0, v94
	v_rcp_f32_e32 v94, v94
	v_lshlrev_b32_e32 v123, 16, v97
	v_fmamk_f32 v114, v114, 0xbfb8aa3b, v104
	v_and_b32_e32 v95, 0xffff0000, v95
	v_mul_f32_e32 v81, v81, v94
	v_fmamk_f32 v94, v96, 0xbfb8aa3b, v101
	v_exp_f32_e32 v94, v94
	v_exp_f32_e32 v114, v114
	v_and_b32_e32 v97, 0xffff0000, v97
	v_add_f32_e32 v94, 1.0, v94
	v_rcp_f32_e32 v94, v94
	v_add_f32_e32 v114, 1.0, v114
	v_rcp_f32_e32 v114, v114
	v_mul_f32_e32 v77, v77, v94
	v_fmamk_f32 v94, v115, 0xbfb8aa3b, v106
	v_exp_f32_e32 v94, v94
	v_mul_f32_e32 v80, v80, v114
	v_fmamk_f32 v114, v122, 0xbfb8aa3b, v100
	v_add_f32_e32 v94, 1.0, v94
	v_rcp_f32_e32 v94, v94
	v_exp_f32_e32 v114, v114
	v_cvt_pk_bf16_f32 v80, v80, v81
	v_mul_f32_e32 v82, v82, v94
	v_fmamk_f32 v94, v123, 0xbfb8aa3b, v102
	v_exp_f32_e32 v94, v94
	v_add_f32_e32 v114, 1.0, v114
	v_rcp_f32_e32 v114, v114
	v_add_f32_e32 v94, 1.0, v94
	v_rcp_f32_e32 v94, v94
	v_mul_f32_e32 v76, v76, v114
	v_mul_f32_e32 v78, v78, v94
	v_fmamk_f32 v94, v95, 0xbfb8aa3b, v107
	v_exp_f32_e32 v94, v94
	s_waitcnt vmcnt(0)
	v_and_b32_e32 v95, 0xffff0000, v121
	v_add_f32_e32 v94, 1.0, v94
	v_rcp_f32_e32 v94, v94
	s_nop 0
	v_mul_f32_e32 v83, v83, v94
	v_fmamk_f32 v94, v97, 0xbfb8aa3b, v103
	v_exp_f32_e32 v94, v94
	v_cvt_pk_bf16_f32 v81, v82, v83
	v_cvt_pk_bf16_f32 v82, v76, v77
	v_lshlrev_b64 v[76:77], 12, v[98:99]
	v_add_f32_e32 v94, 1.0, v94
	v_rcp_f32_e32 v94, v94
	v_lshl_add_u64 v[76:77], s[44:45], 0, v[76:77]
	v_mul_f32_e32 v79, v79, v94
	v_cvt_pk_bf16_f32 v83, v78, v79
	v_lshl_add_u64 v[78:79], v[76:77], 0, v[162:163]
	v_lshlrev_b32_e32 v76, 16, v118
	v_fmamk_f32 v76, v76, 0xbfb8aa3b, v104
	v_exp_f32_e32 v76, v76
	global_store_dwordx4 v[78:79], v[80:83], off
	v_and_b32_e32 v77, 0xffff0000, v118
	v_lshlrev_b32_e32 v94, 16, v121
	v_add_f32_e32 v76, 1.0, v76
	v_rcp_f32_e32 v76, v76
	v_lshlrev_b32_e32 v82, 16, v120
	v_and_b32_e32 v83, 0xffff0000, v120
	v_lshlrev_b32_e32 v80, 16, v119
	v_mul_f32_e32 v72, v72, v76
	v_fmamk_f32 v76, v82, 0xbfb8aa3b, v100
	v_exp_f32_e32 v76, v76
	v_and_b32_e32 v81, 0xffff0000, v119
	v_add_f32_e32 v76, 1.0, v76
	v_rcp_f32_e32 v76, v76
	s_nop 0
	v_mul_f32_e32 v76, v68, v76
	v_fmamk_f32 v68, v77, 0xbfb8aa3b, v105
	v_exp_f32_e32 v68, v68
	s_nop 0
	v_add_f32_e32 v68, 1.0, v68
	v_rcp_f32_e32 v68, v68
	s_nop 0
	v_mul_f32_e32 v68, v73, v68
	v_fmamk_f32 v73, v83, 0xbfb8aa3b, v101
	v_exp_f32_e32 v73, v73
	v_cvt_pk_bf16_f32 v68, v72, v68
	s_nop 0
	v_add_f32_e32 v73, 1.0, v73
	v_rcp_f32_e32 v73, v73
	s_nop 0
	v_mul_f32_e32 v73, v69, v73
	v_fmamk_f32 v69, v80, 0xbfb8aa3b, v106
	v_exp_f32_e32 v69, v69
	v_or_b32_e32 v80, 0x80, v154
	v_add_f32_e32 v69, 1.0, v69
	v_rcp_f32_e32 v69, v69
	s_nop 0
	v_mul_f32_e32 v69, v74, v69
	v_fmamk_f32 v74, v94, 0xbfb8aa3b, v102
	v_exp_f32_e32 v74, v74
	s_nop 0
	v_add_f32_e32 v74, 1.0, v74
	v_rcp_f32_e32 v74, v74
	s_nop 0
	v_mul_f32_e32 v74, v70, v74
	v_fmamk_f32 v70, v81, 0xbfb8aa3b, v107
	v_exp_f32_e32 v70, v70
	v_ashrrev_i32_e32 v81, 31, v80
	v_lshlrev_b64 v[80:81], 1, v[80:81]
	v_lshl_add_u64 v[82:83], v[160:161], 0, v[80:81]
	v_add_f32_e32 v70, 1.0, v70
	v_rcp_f32_e32 v70, v70
	s_nop 0
	v_mul_f32_e32 v70, v75, v70
	v_fmamk_f32 v75, v95, 0xbfb8aa3b, v103
	v_exp_f32_e32 v75, v75
	v_cvt_pk_bf16_f32 v69, v69, v70
	v_cvt_pk_bf16_f32 v70, v76, v73
	v_lshlrev_b64 v[72:73], 12, v[90:91]
	v_add_f32_e32 v75, 1.0, v75
	v_rcp_f32_e32 v75, v75
	v_lshl_add_u64 v[72:73], s[44:45], 0, v[72:73]
	v_lshl_add_u64 v[76:77], v[72:73], 0, v[162:163]
	v_mul_f32_e32 v71, v71, v75
	v_cvt_pk_bf16_f32 v71, v74, v71
	global_store_dwordx4 v[76:77], v[68:71], off
	global_load_dwordx4 v[68:71], v[156:157], off offset:528
	s_nop 0
	global_load_dwordx4 v[72:75], v[156:157], off offset:512
	global_load_dwordx4 v[94:97], v[82:83], off nt
	v_lshl_add_u64 v[82:83], v[158:159], 0, v[80:81]
	global_load_dwordx4 v[98:101], v[82:83], off nt
	s_waitcnt vmcnt(1)
; #define GAS __attribute__((address_space(1)))
; __device__ __forceinline__ void unpack8(const v4u v, float (&f)[8]) { f[0] = bflo(v.x); f[1] = bfhi(v.x); f[2] = bflo(v.y); f[3] = bfhi(v.y); f[4] = bflo(v.z); f[5] = bfhi(v.z); f[6] = bflo(v.w); f[7] = bfhi(v.w); }
; __device__ __forceinline__ v4u pack8(const float (&f)[8]) { v4u o; o.x = cvt_pk_bf16(f[0], f[1]); o.y = cvt_pk_bf16(f[2], f[3]); o.z = cvt_pk_bf16(f[4], f[5]); o.w = cvt_pk_bf16(f[6], f[7]); return o; }
; __device__ __forceinline__ float sigmoidf_(float x) { return __builtin_amdgcn_rcpf(1.f + __expf(-x)); }
;     __device__ __forceinline__ void operator()(const f32x4 (&acc)[2][2][4][2], const pg8::Unit& u, int wr, int wc, int fr, int fq) const {
;     ...
;         for (int bj = 0; bj < 2; ++bj) { const int col = col0 + bj * 128;
;             const f32x4 b0 = *(const GAS f32x4*)(bgate + WHICH * DM + col), b1 = *(const GAS f32x4*)(bgate + WHICH * DM + col + 4);
; #pragma unroll
;             for (int aim = 0; aim < 4; ++aim) { const int ai = aim >> 1, mb = (aim & 1) * 2;
;                 v4u gv[4], tv[4];
; #pragma unroll
;                 for (int m = mb; m < mb + 2; ++m) { const int row = row0 + ai * 128 + m * 16;
;                     gv[m] = __builtin_nontemporal_load((const GAS v4u*)(proj + (size_t)row * NPROJ + OFF_GATE + WHICH * DM + col));
;                     if (WHICH == 1) tv[m] = *(const GAS v4u*)(ta + (size_t)row * DM + col); }
; #pragma unroll
;                 for (int m = mb; m < mb + 2; ++m) { const int row = row0 + ai * 128 + m * 16; float g[8]; unpack8(gv[m], g);
;                     const f32x4 a0 = acc[ai][bj][m][0], a1 = acc[ai][bj][m][1]; float r[8];
; #pragma unroll
;                     for (int e = 0; e < 4; ++e) { r[e] = sigmoidf_(g[e] + b0[e]) * a0[e]; r[4 + e] = sigmoidf_(g[4 + e] + b1[e]) * a1[e]; }
;                     if (WHICH == 0) *(GAS v4u*)(ta + (size_t)row * DM + col) = pack8(r);
;                     else { float tf[8]; unpack8(tv[m], tf);
; #pragma unroll
;                         for (int e = 0; e < 8; ++e) r[e] += tf[e];
;                         *(GAS v4u*)(mix + (size_t)row * DM + col) = pack8(r); } }
	v_lshlrev_b32_e32 v82, 16, v94
	v_mul_f32_e32 v72, 0xbfb8aa3b, v72
	v_fmamk_f32 v82, v82, 0xbfb8aa3b, v72
	v_exp_f32_e32 v82, v82
	v_and_b32_e32 v83, 0xffff0000, v94
	v_lshlrev_b32_e32 v94, 16, v96
	v_lshlrev_b32_e32 v90, 16, v95
	v_add_f32_e32 v82, 1.0, v82
	v_rcp_f32_e32 v82, v82
	v_and_b32_e32 v91, 0xffff0000, v95
	v_and_b32_e32 v95, 0xffff0000, v96
	v_lshlrev_b32_e32 v96, 16, v97
	v_mul_f32_e32 v64, v64, v82
	v_mul_f32_e32 v68, 0xbfb8aa3b, v68
	v_fmamk_f32 v82, v94, 0xbfb8aa3b, v68
	v_exp_f32_e32 v82, v82
	v_and_b32_e32 v97, 0xffff0000, v97
	v_add_f32_e32 v82, 1.0, v82
	v_rcp_f32_e32 v82, v82
	s_nop 0
	v_mul_f32_e32 v82, v60, v82
	v_mul_f32_e32 v73, 0xbfb8aa3b, v73
	v_fmamk_f32 v60, v83, 0xbfb8aa3b, v73
	v_exp_f32_e32 v60, v60
	s_nop 0
	v_add_f32_e32 v60, 1.0, v60
	v_rcp_f32_e32 v60, v60
	s_nop 0
	v_mul_f32_e32 v60, v65, v60
	v_mul_f32_e32 v69, 0xbfb8aa3b, v69
	v_fmamk_f32 v65, v95, 0xbfb8aa3b, v69
	v_exp_f32_e32 v65, v65
	v_cvt_pk_bf16_f32 v60, v64, v60
	s_waitcnt vmcnt(0)
	v_lshlrev_b32_e32 v64, 16, v100
	v_add_f32_e32 v65, 1.0, v65
	v_rcp_f32_e32 v65, v65
	s_nop 0
	v_mul_f32_e32 v65, v61, v65
	v_mul_f32_e32 v74, 0xbfb8aa3b, v74
	v_fmamk_f32 v61, v90, 0xbfb8aa3b, v74
	v_exp_f32_e32 v61, v61
	s_nop 0
	v_add_f32_e32 v61, 1.0, v61
	v_rcp_f32_e32 v61, v61
	s_nop 0
	v_mul_f32_e32 v61, v66, v61
	v_mul_f32_e32 v70, 0xbfb8aa3b, v70
	v_fmamk_f32 v66, v96, 0xbfb8aa3b, v70
	v_exp_f32_e32 v66, v66
	s_nop 0
	v_add_f32_e32 v66, 1.0, v66
	v_rcp_f32_e32 v66, v66
	s_nop 0
	v_mul_f32_e32 v66, v62, v66
	v_mul_f32_e32 v75, 0xbfb8aa3b, v75
	v_fmamk_f32 v62, v91, 0xbfb8aa3b, v75
	v_exp_f32_e32 v62, v62
	s_nop 0
	v_add_f32_e32 v62, 1.0, v62
	v_rcp_f32_e32 v62, v62
	s_nop 0
	v_mul_f32_e32 v62, v67, v62
	v_mul_f32_e32 v71, 0xbfb8aa3b, v71
	v_fmamk_f32 v67, v97, 0xbfb8aa3b, v71
	v_exp_f32_e32 v67, v67
	v_cvt_pk_bf16_f32 v61, v61, v62
	v_cvt_pk_bf16_f32 v62, v82, v65
	v_and_b32_e32 v65, 0xffff0000, v100
	v_add_f32_e32 v67, 1.0, v67
	v_rcp_f32_e32 v67, v67
	s_nop 0
	v_mul_f32_e32 v63, v63, v67
	v_cvt_pk_bf16_f32 v63, v66, v63
	global_store_dwordx4 v[136:137], v[60:63], off offset:256
	v_lshlrev_b32_e32 v66, 16, v101
	v_and_b32_e32 v67, 0xffff0000, v101
	v_lshlrev_b32_e32 v60, 16, v98
	v_fmamk_f32 v60, v60, 0xbfb8aa3b, v72
	v_exp_f32_e32 v60, v60
	v_and_b32_e32 v61, 0xffff0000, v98
	v_lshlrev_b32_e32 v62, 16, v99
	v_and_b32_e32 v63, 0xffff0000, v99
	v_add_f32_e32 v60, 1.0, v60
	v_rcp_f32_e32 v60, v60
	s_nop 0
	v_mul_f32_e32 v56, v56, v60
	v_fmamk_f32 v60, v64, 0xbfb8aa3b, v68
	v_exp_f32_e32 v60, v60
	s_nop 0
	v_add_f32_e32 v60, 1.0, v60
	v_rcp_f32_e32 v60, v60
	s_nop 0
	v_mul_f32_e32 v60, v52, v60
	v_fmamk_f32 v52, v61, 0xbfb8aa3b, v73
	v_exp_f32_e32 v52, v52
	s_nop 0
	v_add_f32_e32 v52, 1.0, v52
	v_rcp_f32_e32 v52, v52
	s_nop 0
	v_mul_f32_e32 v52, v57, v52
	v_fmamk_f32 v57, v65, 0xbfb8aa3b, v69
	v_exp_f32_e32 v57, v57
	v_cvt_pk_bf16_f32 v52, v56, v52
	s_nop 0
	v_add_f32_e32 v57, 1.0, v57
	v_rcp_f32_e32 v57, v57
	s_nop 0
	v_mul_f32_e32 v57, v53, v57
	v_fmamk_f32 v53, v62, 0xbfb8aa3b, v74
	v_exp_f32_e32 v53, v53
	s_nop 0
	v_add_f32_e32 v53, 1.0, v53
	v_rcp_f32_e32 v53, v53
	s_nop 0
	v_mul_f32_e32 v53, v58, v53
	v_fmamk_f32 v58, v66, 0xbfb8aa3b, v70
	v_exp_f32_e32 v58, v58
	s_nop 0
	v_add_f32_e32 v58, 1.0, v58
	v_rcp_f32_e32 v58, v58
	s_nop 0
	v_mul_f32_e32 v58, v54, v58
	v_fmamk_f32 v54, v63, 0xbfb8aa3b, v75
	v_exp_f32_e32 v54, v54
	s_nop 0
	v_add_f32_e32 v54, 1.0, v54
	v_rcp_f32_e32 v54, v54
	s_nop 0
	v_mul_f32_e32 v54, v59, v54
	v_fmamk_f32 v59, v67, 0xbfb8aa3b, v71
	v_exp_f32_e32 v59, v59
	v_cvt_pk_bf16_f32 v53, v53, v54
	v_cvt_pk_bf16_f32 v54, v60, v57
	v_lshl_add_u64 v[56:57], v[132:133], 0, v[80:81]
	v_add_f32_e32 v59, 1.0, v59
	v_rcp_f32_e32 v59, v59
	s_nop 0
	v_mul_f32_e32 v55, v55, v59
	v_cvt_pk_bf16_f32 v55, v58, v55
	global_store_dwordx4 v[128:129], v[52:55], off offset:256
	global_load_dwordx4 v[56:59], v[56:57], off nt
	s_nop 0
	v_lshl_add_u64 v[52:53], v[130:131], 0, v[80:81]
	global_load_dwordx4 v[52:55], v[52:53], off nt
	s_waitcnt vmcnt(0)
	v_lshlrev_b32_e32 v60, 16, v52
	v_fmamk_f32 v60, v60, 0xbfb8aa3b, v72
	v_exp_f32_e32 v60, v60
	v_lshlrev_b32_e32 v62, 16, v54
	v_and_b32_e32 v52, 0xffff0000, v52
	v_and_b32_e32 v54, 0xffff0000, v54
	v_add_f32_e32 v60, 1.0, v60
	v_rcp_f32_e32 v60, v60
	v_lshlrev_b32_e32 v61, 16, v53
	v_lshlrev_b32_e32 v63, 16, v55
	v_and_b32_e32 v53, 0xffff0000, v53
	v_mul_f32_e32 v48, v48, v60
	v_fmamk_f32 v60, v62, 0xbfb8aa3b, v68
	v_exp_f32_e32 v60, v60
	v_and_b32_e32 v55, 0xffff0000, v55
	v_add_f32_e32 v60, 1.0, v60
	v_rcp_f32_e32 v60, v60
	s_nop 0
	v_mul_f32_e32 v60, v44, v60
	v_fmamk_f32 v44, v52, 0xbfb8aa3b, v73
	v_exp_f32_e32 v44, v44
	s_nop 0
	v_add_f32_e32 v44, 1.0, v44
	v_rcp_f32_e32 v44, v44
	s_nop 0
	v_mul_f32_e32 v44, v49, v44
	v_fmamk_f32 v49, v54, 0xbfb8aa3b, v69
	v_exp_f32_e32 v49, v49
	v_cvt_pk_bf16_f32 v44, v48, v44
	v_lshlrev_b32_e32 v48, 16, v58
	v_add_f32_e32 v49, 1.0, v49
	v_rcp_f32_e32 v49, v49
	s_nop 0
	v_mul_f32_e32 v49, v45, v49
	v_fmamk_f32 v45, v61, 0xbfb8aa3b, v74
	v_exp_f32_e32 v45, v45
	s_nop 0
	v_add_f32_e32 v45, 1.0, v45
	v_rcp_f32_e32 v45, v45
	s_nop 0
	v_mul_f32_e32 v45, v50, v45
	v_fmamk_f32 v50, v63, 0xbfb8aa3b, v70
	v_exp_f32_e32 v50, v50
	s_nop 0
	v_add_f32_e32 v50, 1.0, v50
	v_rcp_f32_e32 v50, v50
	s_nop 0
	v_mul_f32_e32 v50, v46, v50
	v_fmamk_f32 v46, v53, 0xbfb8aa3b, v75
	v_exp_f32_e32 v46, v46
	s_nop 0
	v_add_f32_e32 v46, 1.0, v46
	v_rcp_f32_e32 v46, v46
	s_nop 0
	v_mul_f32_e32 v46, v51, v46
	v_fmamk_f32 v51, v55, 0xbfb8aa3b, v71
	v_exp_f32_e32 v51, v51
	v_cvt_pk_bf16_f32 v45, v45, v46
	v_cvt_pk_bf16_f32 v46, v60, v49
	v_and_b32_e32 v49, 0xffff0000, v58
	v_add_f32_e32 v51, 1.0, v51
; #define GAS __attribute__((address_space(1)))
; __device__ __forceinline__ void unpack8(const v4u v, float (&f)[8]) { f[0] = bflo(v.x); f[1] = bfhi(v.x); f[2] = bflo(v.y); f[3] = bfhi(v.y); f[4] = bflo(v.z); f[5] = bfhi(v.z); f[6] = bflo(v.w); f[7] = bfhi(v.w); }
; __device__ __forceinline__ v4u pack8(const float (&f)[8]) { v4u o; o.x = cvt_pk_bf16(f[0], f[1]); o.y = cvt_pk_bf16(f[2], f[3]); o.z = cvt_pk_bf16(f[4], f[5]); o.w = cvt_pk_bf16(f[6], f[7]); return o; }
; __device__ __forceinline__ float sigmoidf_(float x) { return __builtin_amdgcn_rcpf(1.f + __expf(-x)); }
;     __device__ __forceinline__ void operator()(const f32x4 (&acc)[2][2][4][2], const pg8::Unit& u, int wr, int wc, int fr, int fq) const {
;     ...
;             for (int aim = 0; aim < 4; ++aim) { const int ai = aim >> 1, mb = (aim & 1) * 2;
;                 v4u gv[4], tv[4];
; #pragma unroll
;                 for (int m = mb; m < mb + 2; ++m) { const int row = row0 + ai * 128 + m * 16;
;                     gv[m] = __builtin_nontemporal_load((const GAS v4u*)(proj + (size_t)row * NPROJ + OFF_GATE + WHICH * DM + col));
;                     if (WHICH == 1) tv[m] = *(const GAS v4u*)(ta + (size_t)row * DM + col); }
; #pragma unroll
;                 for (int m = mb; m < mb + 2; ++m) { const int row = row0 + ai * 128 + m * 16; float g[8]; unpack8(gv[m], g);
;                     const f32x4 a0 = acc[ai][bj][m][0], a1 = acc[ai][bj][m][1]; float r[8];
; #pragma unroll
;                     for (int e = 0; e < 4; ++e) { r[e] = sigmoidf_(g[e] + b0[e]) * a0[e]; r[4 + e] = sigmoidf_(g[4 + e] + b1[e]) * a1[e]; }
;                     if (WHICH == 0) *(GAS v4u*)(ta + (size_t)row * DM + col) = pack8(r);
;                     else { float tf[8]; unpack8(tv[m], tf);
; #pragma unroll
;                         for (int e = 0; e < 8; ++e) r[e] += tf[e];
;                         *(GAS v4u*)(mix + (size_t)row * DM + col) = pack8(r); } }
	v_rcp_f32_e32 v51, v51
	s_nop 0
	v_mul_f32_e32 v47, v47, v51
	v_cvt_pk_bf16_f32 v47, v50, v47
	global_store_dwordx4 v[116:117], v[44:47], off offset:256
	v_lshlrev_b32_e32 v50, 16, v59
	v_and_b32_e32 v51, 0xffff0000, v59
	v_lshlrev_b32_e32 v44, 16, v56
	v_fmamk_f32 v44, v44, 0xbfb8aa3b, v72
	v_exp_f32_e32 v44, v44
	v_and_b32_e32 v45, 0xffff0000, v56
	v_lshlrev_b32_e32 v46, 16, v57
	v_and_b32_e32 v47, 0xffff0000, v57
	v_add_f32_e32 v44, 1.0, v44
	v_rcp_f32_e32 v44, v44
	s_nop 0
	v_mul_f32_e32 v40, v40, v44
	v_fmamk_f32 v44, v48, 0xbfb8aa3b, v68
	v_exp_f32_e32 v44, v44
	s_nop 0
	v_add_f32_e32 v44, 1.0, v44
	v_rcp_f32_e32 v44, v44
	s_nop 0
	v_mul_f32_e32 v44, v36, v44
	v_fmamk_f32 v36, v45, 0xbfb8aa3b, v73
	v_exp_f32_e32 v36, v36
	s_nop 0
	v_add_f32_e32 v36, 1.0, v36
	v_rcp_f32_e32 v36, v36
	s_nop 0
	v_mul_f32_e32 v36, v41, v36
	v_fmamk_f32 v41, v49, 0xbfb8aa3b, v69
	v_exp_f32_e32 v41, v41
	v_cvt_pk_bf16_f32 v36, v40, v36
	s_nop 0
	v_add_f32_e32 v41, 1.0, v41
	v_rcp_f32_e32 v41, v41
	s_nop 0
	v_mul_f32_e32 v41, v37, v41
	v_fmamk_f32 v37, v46, 0xbfb8aa3b, v74
	v_exp_f32_e32 v37, v37
	s_nop 0
	v_add_f32_e32 v37, 1.0, v37
	v_rcp_f32_e32 v37, v37
	s_nop 0
	v_mul_f32_e32 v37, v42, v37
	v_fmamk_f32 v42, v50, 0xbfb8aa3b, v70
	v_exp_f32_e32 v42, v42
	s_nop 0
	v_add_f32_e32 v42, 1.0, v42
	v_rcp_f32_e32 v42, v42
	s_nop 0
	v_mul_f32_e32 v42, v38, v42
	v_fmamk_f32 v38, v47, 0xbfb8aa3b, v75
	v_exp_f32_e32 v38, v38
	s_nop 0
	v_add_f32_e32 v38, 1.0, v38
	v_rcp_f32_e32 v38, v38
	s_nop 0
	v_mul_f32_e32 v38, v43, v38
	v_fmamk_f32 v43, v51, 0xbfb8aa3b, v71
	v_exp_f32_e32 v43, v43
	v_cvt_pk_bf16_f32 v37, v37, v38
	v_cvt_pk_bf16_f32 v38, v44, v41
	v_lshl_add_u64 v[40:41], v[112:113], 0, v[80:81]
	v_add_f32_e32 v43, 1.0, v43
	v_rcp_f32_e32 v43, v43
	s_nop 0
	v_mul_f32_e32 v39, v39, v43
	v_cvt_pk_bf16_f32 v39, v42, v39
	global_store_dwordx4 v[108:109], v[36:39], off offset:256
	global_load_dwordx4 v[40:43], v[40:41], off nt
	s_nop 0
	v_lshl_add_u64 v[36:37], v[110:111], 0, v[80:81]
	global_load_dwordx4 v[36:39], v[36:37], off nt
	s_waitcnt vmcnt(0)
	v_lshlrev_b32_e32 v44, 16, v36
	v_fmamk_f32 v44, v44, 0xbfb8aa3b, v72
	v_exp_f32_e32 v44, v44
	v_lshlrev_b32_e32 v46, 16, v38
	v_and_b32_e32 v36, 0xffff0000, v36
	v_and_b32_e32 v38, 0xffff0000, v38
	v_add_f32_e32 v44, 1.0, v44
	v_rcp_f32_e32 v44, v44
	v_lshlrev_b32_e32 v45, 16, v37
	v_lshlrev_b32_e32 v47, 16, v39
	v_and_b32_e32 v37, 0xffff0000, v37
	v_mul_f32_e32 v32, v32, v44
	v_fmamk_f32 v44, v46, 0xbfb8aa3b, v68
	v_exp_f32_e32 v44, v44
	v_and_b32_e32 v39, 0xffff0000, v39
	v_add_f32_e32 v44, 1.0, v44
	v_rcp_f32_e32 v44, v44
	s_nop 0
	v_mul_f32_e32 v44, v28, v44
	v_fmamk_f32 v28, v36, 0xbfb8aa3b, v73
	v_exp_f32_e32 v28, v28
	s_nop 0
	v_add_f32_e32 v28, 1.0, v28
	v_rcp_f32_e32 v28, v28
	s_nop 0
	v_mul_f32_e32 v28, v33, v28
	v_fmamk_f32 v33, v38, 0xbfb8aa3b, v69
	v_exp_f32_e32 v33, v33
	v_cvt_pk_bf16_f32 v28, v32, v28
	v_lshlrev_b32_e32 v32, 16, v42
	v_add_f32_e32 v33, 1.0, v33
	v_rcp_f32_e32 v33, v33
	s_nop 0
	v_mul_f32_e32 v33, v29, v33
	v_fmamk_f32 v29, v45, 0xbfb8aa3b, v74
	v_exp_f32_e32 v29, v29
	s_nop 0
	v_add_f32_e32 v29, 1.0, v29
	v_rcp_f32_e32 v29, v29
	s_nop 0
	v_mul_f32_e32 v29, v34, v29
	v_fmamk_f32 v34, v47, 0xbfb8aa3b, v70
	v_exp_f32_e32 v34, v34
	s_nop 0
	v_add_f32_e32 v34, 1.0, v34
	v_rcp_f32_e32 v34, v34
	s_nop 0
	v_mul_f32_e32 v34, v30, v34
	v_fmamk_f32 v30, v37, 0xbfb8aa3b, v75
	v_exp_f32_e32 v30, v30
	s_nop 0
	v_add_f32_e32 v30, 1.0, v30
	v_rcp_f32_e32 v30, v30
	s_nop 0
	v_mul_f32_e32 v30, v35, v30
	v_fmamk_f32 v35, v39, 0xbfb8aa3b, v71
	v_exp_f32_e32 v35, v35
	v_cvt_pk_bf16_f32 v29, v29, v30
	v_cvt_pk_bf16_f32 v30, v44, v33
	v_and_b32_e32 v33, 0xffff0000, v42
	v_add_f32_e32 v35, 1.0, v35
	v_rcp_f32_e32 v35, v35
	s_nop 0
	v_mul_f32_e32 v31, v31, v35
	v_cvt_pk_bf16_f32 v31, v34, v31
	global_store_dwordx4 v[92:93], v[28:31], off offset:256
	v_lshlrev_b32_e32 v34, 16, v43
	v_and_b32_e32 v35, 0xffff0000, v43
	v_lshlrev_b32_e32 v28, 16, v40
	v_fmamk_f32 v28, v28, 0xbfb8aa3b, v72
	v_exp_f32_e32 v28, v28
	v_and_b32_e32 v29, 0xffff0000, v40
	v_lshlrev_b32_e32 v30, 16, v41
	v_and_b32_e32 v31, 0xffff0000, v41
	v_add_f32_e32 v28, 1.0, v28
	v_rcp_f32_e32 v28, v28
	s_nop 0
	v_mul_f32_e32 v24, v24, v28
	v_fmamk_f32 v28, v32, 0xbfb8aa3b, v68
	v_exp_f32_e32 v28, v28
	s_nop 0
	v_add_f32_e32 v28, 1.0, v28
	v_rcp_f32_e32 v28, v28
	s_nop 0
	v_mul_f32_e32 v28, v20, v28
	v_fmamk_f32 v20, v29, 0xbfb8aa3b, v73
	v_exp_f32_e32 v20, v20
	s_nop 0
	v_add_f32_e32 v20, 1.0, v20
	v_rcp_f32_e32 v20, v20
	s_nop 0
	v_mul_f32_e32 v20, v25, v20
	v_fmamk_f32 v25, v33, 0xbfb8aa3b, v69
	v_exp_f32_e32 v25, v25
	v_cvt_pk_bf16_f32 v20, v24, v20
	s_nop 0
	v_add_f32_e32 v25, 1.0, v25
	v_rcp_f32_e32 v25, v25
	s_nop 0
	v_mul_f32_e32 v25, v21, v25
	v_fmamk_f32 v21, v30, 0xbfb8aa3b, v74
	v_exp_f32_e32 v21, v21
	s_nop 0
	v_add_f32_e32 v21, 1.0, v21
	v_rcp_f32_e32 v21, v21
	s_nop 0
	v_mul_f32_e32 v21, v26, v21
	v_fmamk_f32 v26, v34, 0xbfb8aa3b, v70
	v_exp_f32_e32 v26, v26
	s_nop 0
	v_add_f32_e32 v26, 1.0, v26
	v_rcp_f32_e32 v26, v26
	s_nop 0
	v_mul_f32_e32 v26, v22, v26
	v_fmamk_f32 v22, v31, 0xbfb8aa3b, v75
	v_exp_f32_e32 v22, v22
	s_nop 0
	v_add_f32_e32 v22, 1.0, v22
	v_rcp_f32_e32 v22, v22
	s_nop 0
	v_mul_f32_e32 v22, v27, v22
	v_fmamk_f32 v27, v35, 0xbfb8aa3b, v71
	v_exp_f32_e32 v27, v27
	v_cvt_pk_bf16_f32 v21, v21, v22
	v_cvt_pk_bf16_f32 v22, v28, v25
	v_lshl_add_u64 v[24:25], v[88:89], 0, v[80:81]
	v_add_f32_e32 v27, 1.0, v27
	v_rcp_f32_e32 v27, v27
	s_nop 0
	v_mul_f32_e32 v23, v23, v27
	v_cvt_pk_bf16_f32 v23, v26, v23
	global_store_dwordx4 v[84:85], v[20:23], off offset:256
	global_load_dwordx4 v[24:27], v[24:25], off nt
	s_nop 0
	v_lshl_add_u64 v[20:21], v[86:87], 0, v[80:81]
	global_load_dwordx4 v[20:23], v[20:21], off nt
	s_waitcnt vmcnt(0)
; #define GAS __attribute__((address_space(1)))
; __device__ __forceinline__ void unpack8(const v4u v, float (&f)[8]) { f[0] = bflo(v.x); f[1] = bfhi(v.x); f[2] = bflo(v.y); f[3] = bfhi(v.y); f[4] = bflo(v.z); f[5] = bfhi(v.z); f[6] = bflo(v.w); f[7] = bfhi(v.w); }
; __device__ __forceinline__ v4u pack8(const float (&f)[8]) { v4u o; o.x = cvt_pk_bf16(f[0], f[1]); o.y = cvt_pk_bf16(f[2], f[3]); o.z = cvt_pk_bf16(f[4], f[5]); o.w = cvt_pk_bf16(f[6], f[7]); return o; }
; __device__ __forceinline__ float sigmoidf_(float x) { return __builtin_amdgcn_rcpf(1.f + __expf(-x)); }
;     __device__ __forceinline__ void operator()(const f32x4 (&acc)[2][2][4][2], const pg8::Unit& u, int wr, int wc, int fr, int fq) const {
;     ...
;             for (int aim = 0; aim < 4; ++aim) { const int ai = aim >> 1, mb = (aim & 1) * 2;
;                 v4u gv[4], tv[4];
; #pragma unroll
;                 for (int m = mb; m < mb + 2; ++m) { const int row = row0 + ai * 128 + m * 16;
;                     gv[m] = __builtin_nontemporal_load((const GAS v4u*)(proj + (size_t)row * NPROJ + OFF_GATE + WHICH * DM + col));
;                     if (WHICH == 1) tv[m] = *(const GAS v4u*)(ta + (size_t)row * DM + col); }
; #pragma unroll
;                 for (int m = mb; m < mb + 2; ++m) { const int row = row0 + ai * 128 + m * 16; float g[8]; unpack8(gv[m], g);
;                     const f32x4 a0 = acc[ai][bj][m][0], a1 = acc[ai][bj][m][1]; float r[8];
; #pragma unroll
;                     for (int e = 0; e < 4; ++e) { r[e] = sigmoidf_(g[e] + b0[e]) * a0[e]; r[4 + e] = sigmoidf_(g[4 + e] + b1[e]) * a1[e]; }
;                     if (WHICH == 0) *(GAS v4u*)(ta + (size_t)row * DM + col) = pack8(r);
;                     else { float tf[8]; unpack8(tv[m], tf);
; #pragma unroll
;                         for (int e = 0; e < 8; ++e) r[e] += tf[e];
;                         *(GAS v4u*)(mix + (size_t)row * DM + col) = pack8(r); } }
	v_lshlrev_b32_e32 v28, 16, v20
	v_fmamk_f32 v28, v28, 0xbfb8aa3b, v72
	v_exp_f32_e32 v28, v28
	v_lshlrev_b32_e32 v30, 16, v22
	v_and_b32_e32 v20, 0xffff0000, v20
	v_and_b32_e32 v22, 0xffff0000, v22
	v_add_f32_e32 v28, 1.0, v28
	v_rcp_f32_e32 v28, v28
	v_lshlrev_b32_e32 v29, 16, v21
	v_lshlrev_b32_e32 v31, 16, v23
	v_and_b32_e32 v21, 0xffff0000, v21
	v_mul_f32_e32 v16, v16, v28
	v_fmamk_f32 v28, v30, 0xbfb8aa3b, v68
	v_exp_f32_e32 v28, v28
	v_and_b32_e32 v23, 0xffff0000, v23
	v_add_f32_e32 v28, 1.0, v28
	v_rcp_f32_e32 v28, v28
	s_nop 0
	v_mul_f32_e32 v28, v12, v28
	v_fmamk_f32 v12, v20, 0xbfb8aa3b, v73
	v_exp_f32_e32 v12, v12
	s_nop 0
	v_add_f32_e32 v12, 1.0, v12
	v_rcp_f32_e32 v12, v12
	s_nop 0
	v_mul_f32_e32 v12, v17, v12
	v_fmamk_f32 v17, v22, 0xbfb8aa3b, v69
	v_exp_f32_e32 v17, v17
	v_cvt_pk_bf16_f32 v12, v16, v12
	v_lshlrev_b32_e32 v16, 16, v26
	v_add_f32_e32 v17, 1.0, v17
	v_rcp_f32_e32 v17, v17
	s_nop 0
	v_mul_f32_e32 v17, v13, v17
	v_fmamk_f32 v13, v29, 0xbfb8aa3b, v74
	v_exp_f32_e32 v13, v13
	s_nop 0
	v_add_f32_e32 v13, 1.0, v13
	v_rcp_f32_e32 v13, v13
	s_nop 0
	v_mul_f32_e32 v13, v18, v13
	v_fmamk_f32 v18, v31, 0xbfb8aa3b, v70
	v_exp_f32_e32 v18, v18
	s_nop 0
	v_add_f32_e32 v18, 1.0, v18
	v_rcp_f32_e32 v18, v18
	s_nop 0
	v_mul_f32_e32 v18, v14, v18
	v_fmamk_f32 v14, v21, 0xbfb8aa3b, v75
	v_exp_f32_e32 v14, v14
	s_nop 0
	v_add_f32_e32 v14, 1.0, v14
	v_rcp_f32_e32 v14, v14
	s_nop 0
	v_mul_f32_e32 v14, v19, v14
	v_fmamk_f32 v19, v23, 0xbfb8aa3b, v71
	v_exp_f32_e32 v19, v19
	v_cvt_pk_bf16_f32 v13, v13, v14
	v_cvt_pk_bf16_f32 v14, v28, v17
	v_and_b32_e32 v17, 0xffff0000, v26
	v_add_f32_e32 v19, 1.0, v19
	v_rcp_f32_e32 v19, v19
	s_nop 0
	v_mul_f32_e32 v15, v15, v19
	v_cvt_pk_bf16_f32 v15, v18, v15
	global_store_dwordx4 v[78:79], v[12:15], off offset:256
	v_lshlrev_b32_e32 v18, 16, v27
	v_and_b32_e32 v19, 0xffff0000, v27
	v_lshlrev_b32_e32 v12, 16, v24
	v_fmamk_f32 v12, v12, 0xbfb8aa3b, v72
	v_exp_f32_e32 v12, v12
	v_and_b32_e32 v13, 0xffff0000, v24
	v_lshlrev_b32_e32 v14, 16, v25
	v_and_b32_e32 v15, 0xffff0000, v25
	v_add_f32_e32 v12, 1.0, v12
	v_rcp_f32_e32 v12, v12
	s_nop 0
	v_mul_f32_e32 v8, v8, v12
	v_fmamk_f32 v12, v16, 0xbfb8aa3b, v68
	v_exp_f32_e32 v12, v12
	s_nop 0
	v_add_f32_e32 v12, 1.0, v12
	v_rcp_f32_e32 v12, v12
	s_nop 0
	v_mul_f32_e32 v12, v4, v12
	v_fmamk_f32 v4, v13, 0xbfb8aa3b, v73
	v_exp_f32_e32 v4, v4
	s_nop 0
	v_add_f32_e32 v4, 1.0, v4
	v_rcp_f32_e32 v4, v4
	s_nop 0
	v_mul_f32_e32 v4, v9, v4
	v_fmamk_f32 v9, v17, 0xbfb8aa3b, v69
	v_exp_f32_e32 v9, v9
	v_cvt_pk_bf16_f32 v4, v8, v4
	s_nop 0
	v_add_f32_e32 v9, 1.0, v9
	v_rcp_f32_e32 v9, v9
	s_nop 0
	v_mul_f32_e32 v9, v5, v9
	v_fmamk_f32 v5, v14, 0xbfb8aa3b, v74
	v_exp_f32_e32 v5, v5
	s_nop 0
	v_add_f32_e32 v5, 1.0, v5
	v_rcp_f32_e32 v5, v5
	s_nop 0
	v_mul_f32_e32 v5, v10, v5
	v_fmamk_f32 v10, v18, 0xbfb8aa3b, v70
	v_exp_f32_e32 v10, v10
	s_nop 0
	v_add_f32_e32 v10, 1.0, v10
	v_rcp_f32_e32 v10, v10
	s_nop 0
	v_mul_f32_e32 v10, v6, v10
	v_fmamk_f32 v6, v15, 0xbfb8aa3b, v75
	v_exp_f32_e32 v6, v6
	s_nop 0
	v_add_f32_e32 v6, 1.0, v6
	v_rcp_f32_e32 v6, v6
	s_nop 0
	v_mul_f32_e32 v6, v11, v6
	v_fmamk_f32 v11, v19, 0xbfb8aa3b, v71
	v_exp_f32_e32 v11, v11
	v_cvt_pk_bf16_f32 v5, v5, v6
	v_cvt_pk_bf16_f32 v6, v12, v9
	s_nop 0
	v_add_f32_e32 v11, 1.0, v11
	v_rcp_f32_e32 v11, v11
	s_nop 0
	v_mul_f32_e32 v7, v7, v11
	v_cvt_pk_bf16_f32 v7, v10, v7
	global_store_dwordx4 v[76:77], v[4:7], off offset:256
	s_cbranch_vccnz .LBB0_399
	s_andn2_b64 vcc, exec, s[36:37]
	s_cbranch_vccnz .LBB0_398
	s_barrier
	s_branch .LBB0_398

; #define GAS __attribute__((address_space(1)))
; __device__ __forceinline__ void unpack8(const v4u v, float (&f)[8]) { f[0] = bflo(v.x); f[1] = bfhi(v.x); f[2] = bflo(v.y); f[3] = bfhi(v.y); f[4] = bflo(v.z); f[5] = bfhi(v.z); f[6] = bflo(v.w); f[7] = bfhi(v.w); }
; __device__ __forceinline__ v4u pack8(const float (&f)[8]) { v4u o; o.x = cvt_pk_bf16(f[0], f[1]); o.y = cvt_pk_bf16(f[2], f[3]); o.z = cvt_pk_bf16(f[4], f[5]); o.w = cvt_pk_bf16(f[6], f[7]); return o; }
; __device__ __forceinline__ float sigmoidf_(float x) { return __builtin_amdgcn_rcpf(1.f + __expf(-x)); }
;     __device__ __forceinline__ void operator()(const f32x4 (&acc)[2][2][4][2], const pg8::Unit& u, int wr, int wc, int fr, int fq) const {
;     ...
;         for (int bj = 0; bj < 2; ++bj) { const int col = col0 + bj * 128;
;             const f32x4 b0 = *(const GAS f32x4*)(bgate + WHICH * DM + col), b1 = *(const GAS f32x4*)(bgate + WHICH * DM + col + 4);
; #pragma unroll
;             for (int aim = 0; aim < 4; ++aim) { const int ai = aim >> 1, mb = (aim & 1) * 2;
;                 v4u gv[4], tv[4];
; #pragma unroll
;                 for (int m = mb; m < mb + 2; ++m) { const int row = row0 + ai * 128 + m * 16;
;                     gv[m] = __builtin_nontemporal_load((const GAS v4u*)(proj + (size_t)row * NPROJ + OFF_GATE + WHICH * DM + col));
;                     if (WHICH == 1) tv[m] = *(const GAS v4u*)(ta + (size_t)row * DM + col); }
; #pragma unroll
;                 for (int m = mb; m < mb + 2; ++m) { const int row = row0 + ai * 128 + m * 16; float g[8]; unpack8(gv[m], g);
;                     const f32x4 a0 = acc[ai][bj][m][0], a1 = acc[ai][bj][m][1]; float r[8];
; #pragma unroll
;                     for (int e = 0; e < 4; ++e) { r[e] = sigmoidf_(g[e] + b0[e]) * a0[e]; r[4 + e] = sigmoidf_(g[4 + e] + b1[e]) * a1[e]; }
;                     if (WHICH == 0) *(GAS v4u*)(ta + (size_t)row * DM + col) = pack8(r);
;                     else { float tf[8]; unpack8(tv[m], tf);
; #pragma unroll
;                         for (int e = 0; e < 8; ++e) r[e] += tf[e];
;                         *(GAS v4u*)(mix + (size_t)row * DM + col) = pack8(r); } }
.LBB0_488:
	v_lshl_add_u32 v170, s22, 8, v179
	v_lshl_or_b32 v158, s9, 8, v189
	v_mov_b64_e32 v[186:187], s[42:43]
	v_ashrrev_i32_e32 v159, 31, v158
	v_readlane_b32 s14, v253, 51
	v_mad_i64_i32 v[140:141], s[0:1], v170, s4, v[186:187]
	s_mov_b64 s[16:17], 0x9000
	v_readlane_b32 s15, v253, 52
	v_lshlrev_b64 v[168:169], 1, v[158:159]
	v_lshl_add_u64 v[162:163], v[140:141], 0, s[16:17]
	v_lshl_add_u64 v[104:105], v[158:159], 2, s[14:15]
	v_lshl_add_u64 v[140:141], v[162:163], 0, v[168:169]
	global_load_dwordx4 v[100:103], v[104:105], off offset:16
	s_nop 0
	global_load_dwordx4 v[104:107], v[104:105], off
	v_ashrrev_i32_e32 v171, 31, v170
	global_load_dwordx4 v[192:195], v[140:141], off nt
	v_lshl_add_u64 v[184:185], s[44:45], 0, v[168:169]
	v_lshlrev_b64 v[160:161], 12, v[170:171]
	v_lshl_add_u64 v[140:141], v[184:185], 0, v[160:161]
	global_load_dwordx4 v[196:199], v[140:141], off
	v_or_b32_e32 v140, 16, v170
	v_mad_i64_i32 v[142:143], s[0:1], v140, s4, v[186:187]
	v_lshl_add_u64 v[164:165], v[142:143], 0, s[16:17]
	v_lshl_add_u64 v[142:143], v[164:165], 0, v[168:169]
	global_load_dwordx4 v[144:147], v[142:143], off nt
	v_ashrrev_i32_e32 v141, 31, v140
	v_lshlrev_b64 v[166:167], 12, v[140:141]
	v_lshl_add_u64 v[140:141], v[184:185], 0, v[166:167]
	global_load_dwordx4 v[140:143], v[140:141], off
	s_andn2_b64 vcc, exec, s[40:41]
	s_waitcnt vmcnt(0)
	v_lshlrev_b32_e32 v159, 16, v192
	v_and_b32_e32 v171, 0xffff0000, v192
	v_lshlrev_b32_e32 v191, 16, v193
	v_and_b32_e32 v192, 0xffff0000, v193
	v_lshlrev_b32_e32 v193, 16, v194
	v_and_b32_e32 v194, 0xffff0000, v194
	v_mul_f32_e32 v104, 0xbfb8aa3b, v104
	v_fmamk_f32 v159, v159, 0xbfb8aa3b, v104
	v_mul_f32_e32 v105, 0xbfb8aa3b, v105
	v_fmamk_f32 v171, v171, 0xbfb8aa3b, v105
	v_lshlrev_b32_e32 v200, 16, v195
	v_and_b32_e32 v195, 0xffff0000, v195
	v_mul_f32_e32 v100, 0xbfb8aa3b, v100
	v_fmamk_f32 v193, v193, 0xbfb8aa3b, v100
	v_mul_f32_e32 v101, 0xbfb8aa3b, v101
	v_fmamk_f32 v194, v194, 0xbfb8aa3b, v101
	v_mul_f32_e32 v106, 0xbfb8aa3b, v106
	v_fmamk_f32 v191, v191, 0xbfb8aa3b, v106
	v_mul_f32_e32 v107, 0xbfb8aa3b, v107
	v_fmamk_f32 v192, v192, 0xbfb8aa3b, v107
	v_exp_f32_e32 v159, v159
	v_exp_f32_e32 v171, v171
	v_mul_f32_e32 v102, 0xbfb8aa3b, v102
	v_fmamk_f32 v200, v200, 0xbfb8aa3b, v102
	v_mul_f32_e32 v103, 0xbfb8aa3b, v103
	v_fmamk_f32 v195, v195, 0xbfb8aa3b, v103
	v_exp_f32_e32 v193, v193
	v_exp_f32_e32 v194, v194
	v_exp_f32_e32 v191, v191
	v_exp_f32_e32 v192, v192
	v_exp_f32_e32 v200, v200
	v_exp_f32_e32 v195, v195
	v_add_f32_e32 v159, 1.0, v159
	v_add_f32_e32 v171, 1.0, v171
	v_rcp_f32_e32 v159, v159
	v_add_f32_e32 v193, 1.0, v193
	v_rcp_f32_e32 v171, v171
	v_add_f32_e32 v194, 1.0, v194
	v_add_f32_e32 v191, 1.0, v191
	v_add_f32_e32 v192, 1.0, v192
	v_rcp_f32_e32 v193, v193
	v_rcp_f32_e32 v194, v194
	v_rcp_f32_e32 v191, v191
	v_add_f32_e32 v200, 1.0, v200
	v_rcp_f32_e32 v192, v192
	v_add_f32_e32 v195, 1.0, v195
	v_rcp_f32_e32 v200, v200
	v_rcp_f32_e32 v195, v195
	v_lshlrev_b32_e32 v201, 16, v196
	v_and_b32_e32 v196, 0xffff0000, v196
	v_lshlrev_b32_e32 v202, 16, v197
	v_and_b32_e32 v197, 0xffff0000, v197
	v_lshlrev_b32_e32 v203, 16, v198
	v_and_b32_e32 v198, 0xffff0000, v198
	v_fmac_f32_e32 v201, v136, v159
	v_fmac_f32_e32 v196, v137, v171
	v_lshl_add_u64 v[136:137], s[46:47], 0, v[160:161]
	v_lshlrev_b32_e32 v204, 16, v199
	v_and_b32_e32 v199, 0xffff0000, v199
	v_fmac_f32_e32 v202, v138, v191
	v_fmac_f32_e32 v197, v139, v192
	v_fmac_f32_e32 v203, v132, v193
	v_fmac_f32_e32 v198, v133, v194
	v_cvt_pk_bf16_f32 v132, v201, v196
	v_cvt_pk_bf16_f32 v133, v202, v197
	v_lshl_add_u64 v[136:137], v[136:137], 0, v[168:169]
	v_fmac_f32_e32 v204, v134, v200
	v_fmac_f32_e32 v199, v135, v195
	v_cvt_pk_bf16_f32 v134, v203, v198
	v_cvt_pk_bf16_f32 v135, v204, v199
	global_store_dwordx4 v[136:137], v[132:135], off
	v_lshlrev_b32_e32 v138, 16, v146
	v_and_b32_e32 v139, 0xffff0000, v146
	v_lshlrev_b32_e32 v132, 16, v144
	v_and_b32_e32 v133, 0xffff0000, v144
	v_fmamk_f32 v132, v132, 0xbfb8aa3b, v104
	v_fmamk_f32 v133, v133, 0xbfb8aa3b, v105
	v_lshlrev_b32_e32 v134, 16, v145
	v_and_b32_e32 v135, 0xffff0000, v145
	v_lshlrev_b32_e32 v144, 16, v147
	v_and_b32_e32 v145, 0xffff0000, v147
	v_fmamk_f32 v138, v138, 0xbfb8aa3b, v100
	v_exp_f32_e32 v132, v132
	v_exp_f32_e32 v133, v133
	v_fmamk_f32 v139, v139, 0xbfb8aa3b, v101
	v_fmamk_f32 v134, v134, 0xbfb8aa3b, v106
	v_fmamk_f32 v144, v144, 0xbfb8aa3b, v102
	v_fmamk_f32 v135, v135, 0xbfb8aa3b, v107
	v_fmamk_f32 v145, v145, 0xbfb8aa3b, v103
	v_exp_f32_e32 v138, v138
	v_exp_f32_e32 v139, v139
	v_exp_f32_e32 v134, v134
	v_exp_f32_e32 v144, v144
	v_exp_f32_e32 v135, v135
	v_exp_f32_e32 v145, v145
	v_add_f32_e32 v132, 1.0, v132
	v_add_f32_e32 v133, 1.0, v133
	v_rcp_f32_e32 v132, v132
	v_add_f32_e32 v138, 1.0, v138
	v_rcp_f32_e32 v133, v133
	v_rcp_f32_e32 v138, v138
	v_add_f32_e32 v139, 1.0, v139
	v_add_f32_e32 v134, 1.0, v134
	v_add_f32_e32 v144, 1.0, v144
	v_add_f32_e32 v135, 1.0, v135
	v_add_f32_e32 v145, 1.0, v145
	v_rcp_f32_e32 v139, v139
	v_rcp_f32_e32 v134, v134
	v_rcp_f32_e32 v144, v144
	v_rcp_f32_e32 v135, v135
	v_rcp_f32_e32 v145, v145
	v_lshlrev_b32_e32 v146, 16, v140
	v_and_b32_e32 v140, 0xffff0000, v140
	v_lshlrev_b32_e32 v159, 16, v142
	v_fmac_f32_e32 v146, v128, v132
	v_fmac_f32_e32 v140, v129, v133
	v_lshl_add_u64 v[128:129], s[46:47], 0, v[166:167]
	v_lshlrev_b32_e32 v147, 16, v141
	v_and_b32_e32 v141, 0xffff0000, v141
	v_and_b32_e32 v142, 0xffff0000, v142
	v_lshlrev_b32_e32 v171, 16, v143
	v_and_b32_e32 v143, 0xffff0000, v143
	v_fmac_f32_e32 v159, v124, v138
	v_cvt_pk_bf16_f32 v124, v146, v140
	v_lshl_add_u64 v[128:129], v[128:129], 0, v[168:169]
	v_fmac_f32_e32 v147, v130, v134
	v_fmac_f32_e32 v141, v131, v135
	v_fmac_f32_e32 v142, v125, v139
	v_fmac_f32_e32 v171, v126, v144
	v_fmac_f32_e32 v143, v127, v145
	v_cvt_pk_bf16_f32 v125, v147, v141
	v_cvt_pk_bf16_f32 v126, v159, v142
	v_cvt_pk_bf16_f32 v127, v171, v143
	global_store_dwordx4 v[128:129], v[124:127], off
	s_nop 1
	v_or_b32_e32 v124, 32, v170
	v_mad_i64_i32 v[126:127], s[0:1], v124, s4, v[186:187]
	v_lshl_add_u64 v[130:131], v[126:127], 0, s[16:17]
	v_lshl_add_u64 v[126:127], v[130:131], 0, v[168:169]
	global_load_dwordx4 v[140:143], v[126:127], off nt
	v_ashrrev_i32_e32 v125, 31, v124
	v_lshlrev_b64 v[132:133], 12, v[124:125]
	v_lshl_add_u64 v[124:125], v[184:185], 0, v[132:133]
	global_load_dwordx4 v[144:147], v[124:125], off
	v_or_b32_e32 v124, 48, v170
	v_mad_i64_i32 v[126:127], s[0:1], v124, s4, v[186:187]
	v_lshl_add_u64 v[134:135], v[126:127], 0, s[16:17]
	v_lshl_add_u64 v[126:127], v[134:135], 0, v[168:169]
	global_load_dwordx4 v[192:195], v[126:127], off nt
	v_ashrrev_i32_e32 v125, 31, v124
	v_lshlrev_b64 v[138:139], 12, v[124:125]
	v_lshl_add_u64 v[124:125], v[184:185], 0, v[138:139]
	global_load_dwordx4 v[124:127], v[124:125], off
	s_waitcnt vmcnt(3)
; #define GAS __attribute__((address_space(1)))
; __device__ __forceinline__ void unpack8(const v4u v, float (&f)[8]) { f[0] = bflo(v.x); f[1] = bfhi(v.x); f[2] = bflo(v.y); f[3] = bfhi(v.y); f[4] = bflo(v.z); f[5] = bfhi(v.z); f[6] = bflo(v.w); f[7] = bfhi(v.w); }
; __device__ __forceinline__ v4u pack8(const float (&f)[8]) { v4u o; o.x = cvt_pk_bf16(f[0], f[1]); o.y = cvt_pk_bf16(f[2], f[3]); o.z = cvt_pk_bf16(f[4], f[5]); o.w = cvt_pk_bf16(f[6], f[7]); return o; }
; __device__ __forceinline__ float sigmoidf_(float x) { return __builtin_amdgcn_rcpf(1.f + __expf(-x)); }
;     __device__ __forceinline__ void operator()(const f32x4 (&acc)[2][2][4][2], const pg8::Unit& u, int wr, int wc, int fr, int fq) const {
;     ...
;             for (int aim = 0; aim < 4; ++aim) { const int ai = aim >> 1, mb = (aim & 1) * 2;
;                 v4u gv[4], tv[4];
; #pragma unroll
;                 for (int m = mb; m < mb + 2; ++m) { const int row = row0 + ai * 128 + m * 16;
;                     gv[m] = __builtin_nontemporal_load((const GAS v4u*)(proj + (size_t)row * NPROJ + OFF_GATE + WHICH * DM + col));
;                     if (WHICH == 1) tv[m] = *(const GAS v4u*)(ta + (size_t)row * DM + col); }
; #pragma unroll
;                 for (int m = mb; m < mb + 2; ++m) { const int row = row0 + ai * 128 + m * 16; float g[8]; unpack8(gv[m], g);
;                     const f32x4 a0 = acc[ai][bj][m][0], a1 = acc[ai][bj][m][1]; float r[8];
; #pragma unroll
;                     for (int e = 0; e < 4; ++e) { r[e] = sigmoidf_(g[e] + b0[e]) * a0[e]; r[4 + e] = sigmoidf_(g[4 + e] + b1[e]) * a1[e]; }
;                     if (WHICH == 0) *(GAS v4u*)(ta + (size_t)row * DM + col) = pack8(r);
;                     else { float tf[8]; unpack8(tv[m], tf);
; #pragma unroll
;                         for (int e = 0; e < 8; ++e) r[e] += tf[e];
;                         *(GAS v4u*)(mix + (size_t)row * DM + col) = pack8(r); } }
	v_lshlrev_b32_e32 v191, 16, v142
	v_and_b32_e32 v142, 0xffff0000, v142
	v_lshlrev_b32_e32 v159, 16, v140
	v_and_b32_e32 v140, 0xffff0000, v140
	v_lshlrev_b32_e32 v171, 16, v141
	v_and_b32_e32 v141, 0xffff0000, v141
	v_lshlrev_b32_e32 v196, 16, v143
	v_and_b32_e32 v143, 0xffff0000, v143
	v_fmamk_f32 v191, v191, 0xbfb8aa3b, v100
	v_fmamk_f32 v142, v142, 0xbfb8aa3b, v101
	v_fmamk_f32 v159, v159, 0xbfb8aa3b, v104
	v_fmamk_f32 v140, v140, 0xbfb8aa3b, v105
	v_fmamk_f32 v171, v171, 0xbfb8aa3b, v106
	v_fmamk_f32 v196, v196, 0xbfb8aa3b, v102
	v_fmamk_f32 v141, v141, 0xbfb8aa3b, v107
	v_fmamk_f32 v143, v143, 0xbfb8aa3b, v103
	v_exp_f32_e32 v191, v191
	v_exp_f32_e32 v142, v142
	v_exp_f32_e32 v159, v159
	v_exp_f32_e32 v140, v140
	v_exp_f32_e32 v171, v171
	v_exp_f32_e32 v196, v196
	v_exp_f32_e32 v141, v141
	v_exp_f32_e32 v143, v143
	v_add_f32_e32 v191, 1.0, v191
	v_add_f32_e32 v142, 1.0, v142
	v_add_f32_e32 v159, 1.0, v159
	v_rcp_f32_e32 v191, v191
	v_add_f32_e32 v140, 1.0, v140
	v_rcp_f32_e32 v142, v142
	v_add_f32_e32 v171, 1.0, v171
	v_add_f32_e32 v196, 1.0, v196
	v_add_f32_e32 v141, 1.0, v141
	v_add_f32_e32 v143, 1.0, v143
	v_rcp_f32_e32 v159, v159
	v_rcp_f32_e32 v140, v140
	v_rcp_f32_e32 v171, v171
	v_rcp_f32_e32 v196, v196
	v_rcp_f32_e32 v141, v141
	v_rcp_f32_e32 v143, v143
	s_waitcnt vmcnt(2)
	v_lshlrev_b32_e32 v199, 16, v146
	v_and_b32_e32 v146, 0xffff0000, v146
	v_lshlrev_b32_e32 v197, 16, v144
	v_and_b32_e32 v144, 0xffff0000, v144
	v_lshlrev_b32_e32 v198, 16, v145
	v_and_b32_e32 v145, 0xffff0000, v145
	v_lshlrev_b32_e32 v200, 16, v147
	v_and_b32_e32 v147, 0xffff0000, v147
	v_fmac_f32_e32 v199, v116, v191
	v_fmac_f32_e32 v146, v117, v142
	v_lshl_add_u64 v[116:117], s[46:47], 0, v[132:133]
	v_fmac_f32_e32 v197, v120, v159
	v_fmac_f32_e32 v144, v121, v140
	v_fmac_f32_e32 v198, v122, v171
	v_fmac_f32_e32 v145, v123, v141
	v_fmac_f32_e32 v200, v118, v196
	v_fmac_f32_e32 v147, v119, v143
	v_cvt_pk_bf16_f32 v118, v197, v144
	v_cvt_pk_bf16_f32 v119, v198, v145
	v_lshl_add_u64 v[116:117], v[116:117], 0, v[168:169]
	v_cvt_pk_bf16_f32 v120, v199, v146
	v_cvt_pk_bf16_f32 v121, v200, v147
	global_store_dwordx4 v[116:117], v[118:121], off
	s_waitcnt vmcnt(2)
	v_lshlrev_b32_e32 v122, 16, v194
	v_and_b32_e32 v123, 0xffff0000, v194
	v_lshlrev_b32_e32 v118, 16, v192
	v_and_b32_e32 v119, 0xffff0000, v192
	v_fmamk_f32 v118, v118, 0xbfb8aa3b, v104
	v_fmamk_f32 v119, v119, 0xbfb8aa3b, v105
	v_lshlrev_b32_e32 v120, 16, v193
	v_and_b32_e32 v121, 0xffff0000, v193
	v_lshlrev_b32_e32 v140, 16, v195
	v_and_b32_e32 v141, 0xffff0000, v195
	v_fmamk_f32 v122, v122, 0xbfb8aa3b, v100
	v_exp_f32_e32 v118, v118
	v_exp_f32_e32 v119, v119
	v_fmamk_f32 v123, v123, 0xbfb8aa3b, v101
	v_fmamk_f32 v120, v120, 0xbfb8aa3b, v106
	v_fmamk_f32 v140, v140, 0xbfb8aa3b, v102
	v_fmamk_f32 v121, v121, 0xbfb8aa3b, v107
	v_fmamk_f32 v141, v141, 0xbfb8aa3b, v103
	v_exp_f32_e32 v122, v122
	v_exp_f32_e32 v123, v123
	v_exp_f32_e32 v120, v120
	v_exp_f32_e32 v140, v140
	v_exp_f32_e32 v121, v121
	v_exp_f32_e32 v141, v141
	v_add_f32_e32 v118, 1.0, v118
	v_add_f32_e32 v119, 1.0, v119
	v_rcp_f32_e32 v118, v118
	v_add_f32_e32 v122, 1.0, v122
	v_rcp_f32_e32 v119, v119
	v_rcp_f32_e32 v122, v122
	v_add_f32_e32 v123, 1.0, v123
	v_add_f32_e32 v120, 1.0, v120
	v_add_f32_e32 v140, 1.0, v140
	v_add_f32_e32 v121, 1.0, v121
	v_add_f32_e32 v141, 1.0, v141
	v_rcp_f32_e32 v123, v123
	v_rcp_f32_e32 v120, v120
	v_rcp_f32_e32 v140, v140
	v_rcp_f32_e32 v121, v121
	v_rcp_f32_e32 v141, v141
	s_waitcnt vmcnt(1)
	v_lshlrev_b32_e32 v142, 16, v124
	v_and_b32_e32 v124, 0xffff0000, v124
	v_lshlrev_b32_e32 v144, 16, v126
	v_fmac_f32_e32 v142, v112, v118
	v_fmac_f32_e32 v124, v113, v119
	v_lshl_add_u64 v[112:113], s[46:47], 0, v[138:139]
	v_lshlrev_b32_e32 v143, 16, v125
	v_and_b32_e32 v125, 0xffff0000, v125
	v_and_b32_e32 v126, 0xffff0000, v126
	v_lshlrev_b32_e32 v145, 16, v127
	v_and_b32_e32 v127, 0xffff0000, v127
	v_fmac_f32_e32 v144, v108, v122
	v_cvt_pk_bf16_f32 v108, v142, v124
	v_lshl_add_u64 v[112:113], v[112:113], 0, v[168:169]
	v_fmac_f32_e32 v143, v114, v120
	v_fmac_f32_e32 v125, v115, v121
	v_fmac_f32_e32 v126, v109, v123
	v_fmac_f32_e32 v145, v110, v140
	v_fmac_f32_e32 v127, v111, v141
	v_cvt_pk_bf16_f32 v109, v143, v125
	v_cvt_pk_bf16_f32 v110, v144, v126
	v_cvt_pk_bf16_f32 v111, v145, v127
	global_store_dwordx4 v[112:113], v[108:111], off
	s_nop 1
	v_add_u32_e32 v108, 0x80, v170
	v_mad_i64_i32 v[110:111], s[0:1], v108, s4, v[186:187]
	v_lshl_add_u64 v[114:115], v[110:111], 0, s[16:17]
	v_lshl_add_u64 v[110:111], v[114:115], 0, v[168:169]
	global_load_dwordx4 v[124:127], v[110:111], off nt
	v_ashrrev_i32_e32 v109, 31, v108
	v_lshlrev_b64 v[118:119], 12, v[108:109]
	v_lshl_add_u64 v[108:109], v[184:185], 0, v[118:119]
	global_load_dwordx4 v[140:143], v[108:109], off
	v_add_u32_e32 v108, 0x90, v170
	v_mad_i64_i32 v[110:111], s[0:1], v108, s4, v[186:187]
	v_lshl_add_u64 v[120:121], v[110:111], 0, s[16:17]
	v_lshl_add_u64 v[110:111], v[120:121], 0, v[168:169]
	global_load_dwordx4 v[144:147], v[110:111], off nt
	v_ashrrev_i32_e32 v109, 31, v108
	v_lshlrev_b64 v[122:123], 12, v[108:109]
	v_lshl_add_u64 v[108:109], v[184:185], 0, v[122:123]
	global_load_dwordx4 v[108:111], v[108:109], off
	s_waitcnt vmcnt(3)
; #define GAS __attribute__((address_space(1)))
; __device__ __forceinline__ void unpack8(const v4u v, float (&f)[8]) { f[0] = bflo(v.x); f[1] = bfhi(v.x); f[2] = bflo(v.y); f[3] = bfhi(v.y); f[4] = bflo(v.z); f[5] = bfhi(v.z); f[6] = bflo(v.w); f[7] = bfhi(v.w); }
; __device__ __forceinline__ v4u pack8(const float (&f)[8]) { v4u o; o.x = cvt_pk_bf16(f[0], f[1]); o.y = cvt_pk_bf16(f[2], f[3]); o.z = cvt_pk_bf16(f[4], f[5]); o.w = cvt_pk_bf16(f[6], f[7]); return o; }
; __device__ __forceinline__ float sigmoidf_(float x) { return __builtin_amdgcn_rcpf(1.f + __expf(-x)); }
;     __device__ __forceinline__ void operator()(const f32x4 (&acc)[2][2][4][2], const pg8::Unit& u, int wr, int wc, int fr, int fq) const {
;     ...
;         for (int bj = 0; bj < 2; ++bj) { const int col = col0 + bj * 128;
;             const f32x4 b0 = *(const GAS f32x4*)(bgate + WHICH * DM + col), b1 = *(const GAS f32x4*)(bgate + WHICH * DM + col + 4);
; #pragma unroll
;             for (int aim = 0; aim < 4; ++aim) { const int ai = aim >> 1, mb = (aim & 1) * 2;
;                 v4u gv[4], tv[4];
; #pragma unroll
;                 for (int m = mb; m < mb + 2; ++m) { const int row = row0 + ai * 128 + m * 16;
;                     gv[m] = __builtin_nontemporal_load((const GAS v4u*)(proj + (size_t)row * NPROJ + OFF_GATE + WHICH * DM + col));
;                     if (WHICH == 1) tv[m] = *(const GAS v4u*)(ta + (size_t)row * DM + col); }
; #pragma unroll
;                 for (int m = mb; m < mb + 2; ++m) { const int row = row0 + ai * 128 + m * 16; float g[8]; unpack8(gv[m], g);
;                     const f32x4 a0 = acc[ai][bj][m][0], a1 = acc[ai][bj][m][1]; float r[8];
; #pragma unroll
;                     for (int e = 0; e < 4; ++e) { r[e] = sigmoidf_(g[e] + b0[e]) * a0[e]; r[4 + e] = sigmoidf_(g[4 + e] + b1[e]) * a1[e]; }
;                     if (WHICH == 0) *(GAS v4u*)(ta + (size_t)row * DM + col) = pack8(r);
;                     else { float tf[8]; unpack8(tv[m], tf);
; #pragma unroll
;                         for (int e = 0; e < 8; ++e) r[e] += tf[e];
;                         *(GAS v4u*)(mix + (size_t)row * DM + col) = pack8(r); } }
	v_lshlrev_b32_e32 v191, 16, v126
	v_and_b32_e32 v126, 0xffff0000, v126
	v_lshlrev_b32_e32 v159, 16, v124
	v_and_b32_e32 v124, 0xffff0000, v124
	v_lshlrev_b32_e32 v171, 16, v125
	v_and_b32_e32 v125, 0xffff0000, v125
	v_lshlrev_b32_e32 v192, 16, v127
	v_and_b32_e32 v127, 0xffff0000, v127
	v_fmamk_f32 v191, v191, 0xbfb8aa3b, v100
	v_fmamk_f32 v126, v126, 0xbfb8aa3b, v101
	v_fmamk_f32 v159, v159, 0xbfb8aa3b, v104
	v_fmamk_f32 v124, v124, 0xbfb8aa3b, v105
	v_fmamk_f32 v171, v171, 0xbfb8aa3b, v106
	v_fmamk_f32 v192, v192, 0xbfb8aa3b, v102
	v_fmamk_f32 v125, v125, 0xbfb8aa3b, v107
	v_fmamk_f32 v127, v127, 0xbfb8aa3b, v103
	v_exp_f32_e32 v191, v191
	v_exp_f32_e32 v126, v126
	v_exp_f32_e32 v159, v159
	v_exp_f32_e32 v124, v124
	v_exp_f32_e32 v171, v171
	v_exp_f32_e32 v192, v192
	v_exp_f32_e32 v125, v125
	v_exp_f32_e32 v127, v127
	v_add_f32_e32 v191, 1.0, v191
	v_add_f32_e32 v126, 1.0, v126
	v_add_f32_e32 v159, 1.0, v159
	v_rcp_f32_e32 v191, v191
	v_add_f32_e32 v124, 1.0, v124
	v_rcp_f32_e32 v126, v126
	v_add_f32_e32 v171, 1.0, v171
	v_add_f32_e32 v192, 1.0, v192
	v_add_f32_e32 v125, 1.0, v125
	v_add_f32_e32 v127, 1.0, v127
	v_rcp_f32_e32 v159, v159
	v_rcp_f32_e32 v124, v124
	v_rcp_f32_e32 v171, v171
	v_rcp_f32_e32 v192, v192
	v_rcp_f32_e32 v125, v125
	v_rcp_f32_e32 v127, v127
	s_waitcnt vmcnt(2)
	v_lshlrev_b32_e32 v195, 16, v142
	v_and_b32_e32 v142, 0xffff0000, v142
	v_lshlrev_b32_e32 v193, 16, v140
	v_and_b32_e32 v140, 0xffff0000, v140
	v_lshlrev_b32_e32 v194, 16, v141
	v_and_b32_e32 v141, 0xffff0000, v141
	v_lshlrev_b32_e32 v196, 16, v143
	v_and_b32_e32 v143, 0xffff0000, v143
	v_fmac_f32_e32 v195, v92, v191
	v_fmac_f32_e32 v142, v93, v126
	v_lshl_add_u64 v[92:93], s[46:47], 0, v[118:119]
	v_fmac_f32_e32 v193, v96, v159
	v_fmac_f32_e32 v140, v97, v124
	v_fmac_f32_e32 v194, v98, v171
	v_fmac_f32_e32 v141, v99, v125
	v_fmac_f32_e32 v196, v94, v192
	v_fmac_f32_e32 v143, v95, v127
	v_cvt_pk_bf16_f32 v94, v193, v140
	v_cvt_pk_bf16_f32 v95, v194, v141
	v_lshl_add_u64 v[92:93], v[92:93], 0, v[168:169]
	v_cvt_pk_bf16_f32 v96, v195, v142
	v_cvt_pk_bf16_f32 v97, v196, v143
	global_store_dwordx4 v[92:93], v[94:97], off
	s_waitcnt vmcnt(2)
	v_lshlrev_b32_e32 v98, 16, v146
	v_and_b32_e32 v99, 0xffff0000, v146
	v_lshlrev_b32_e32 v94, 16, v144
	v_and_b32_e32 v95, 0xffff0000, v144
	v_fmamk_f32 v94, v94, 0xbfb8aa3b, v104
	v_fmamk_f32 v95, v95, 0xbfb8aa3b, v105
	v_lshlrev_b32_e32 v96, 16, v145
	v_and_b32_e32 v97, 0xffff0000, v145
	v_lshlrev_b32_e32 v124, 16, v147
	v_and_b32_e32 v125, 0xffff0000, v147
	v_fmamk_f32 v98, v98, 0xbfb8aa3b, v100
	v_exp_f32_e32 v94, v94
	v_exp_f32_e32 v95, v95
	v_fmamk_f32 v99, v99, 0xbfb8aa3b, v101
	v_fmamk_f32 v96, v96, 0xbfb8aa3b, v106
	v_fmamk_f32 v124, v124, 0xbfb8aa3b, v102
	v_fmamk_f32 v97, v97, 0xbfb8aa3b, v107
	v_fmamk_f32 v125, v125, 0xbfb8aa3b, v103
	v_exp_f32_e32 v98, v98
	v_exp_f32_e32 v99, v99
	v_exp_f32_e32 v96, v96
	v_exp_f32_e32 v124, v124
	v_exp_f32_e32 v97, v97
	v_exp_f32_e32 v125, v125
	v_add_f32_e32 v94, 1.0, v94
	v_add_f32_e32 v95, 1.0, v95
	v_rcp_f32_e32 v94, v94
	v_add_f32_e32 v98, 1.0, v98
	v_rcp_f32_e32 v95, v95
	v_rcp_f32_e32 v98, v98
	v_add_f32_e32 v99, 1.0, v99
	v_add_f32_e32 v96, 1.0, v96
	v_add_f32_e32 v124, 1.0, v124
	v_add_f32_e32 v97, 1.0, v97
	v_add_f32_e32 v125, 1.0, v125
	v_rcp_f32_e32 v99, v99
	v_rcp_f32_e32 v96, v96
	v_rcp_f32_e32 v124, v124
	v_rcp_f32_e32 v97, v97
	v_rcp_f32_e32 v125, v125
	s_waitcnt vmcnt(1)
	v_lshlrev_b32_e32 v126, 16, v108
	v_and_b32_e32 v108, 0xffff0000, v108
	v_lshlrev_b32_e32 v140, 16, v110
	v_fmac_f32_e32 v126, v88, v94
	v_fmac_f32_e32 v108, v89, v95
	v_lshl_add_u64 v[88:89], s[46:47], 0, v[122:123]
	v_lshlrev_b32_e32 v127, 16, v109
	v_and_b32_e32 v109, 0xffff0000, v109
	v_and_b32_e32 v110, 0xffff0000, v110
	v_lshlrev_b32_e32 v141, 16, v111
	v_and_b32_e32 v111, 0xffff0000, v111
	v_fmac_f32_e32 v140, v84, v98
	v_cvt_pk_bf16_f32 v84, v126, v108
	v_lshl_add_u64 v[88:89], v[88:89], 0, v[168:169]
	v_fmac_f32_e32 v127, v90, v96
	v_fmac_f32_e32 v109, v91, v97
	v_fmac_f32_e32 v110, v85, v99
	v_fmac_f32_e32 v141, v86, v124
	v_fmac_f32_e32 v111, v87, v125
	v_cvt_pk_bf16_f32 v85, v127, v109
	v_cvt_pk_bf16_f32 v86, v140, v110
	v_cvt_pk_bf16_f32 v87, v141, v111
	global_store_dwordx4 v[88:89], v[84:87], off
	s_nop 1
	v_add_u32_e32 v84, 0xa0, v170
	v_mad_i64_i32 v[86:87], s[0:1], v84, s4, v[186:187]
	v_lshl_add_u64 v[90:91], v[86:87], 0, s[16:17]
	v_lshl_add_u64 v[86:87], v[90:91], 0, v[168:169]
	global_load_dwordx4 v[108:111], v[86:87], off nt
	v_ashrrev_i32_e32 v85, 31, v84
	v_lshlrev_b64 v[94:95], 12, v[84:85]
	v_lshl_add_u64 v[84:85], v[184:185], 0, v[94:95]
	global_load_dwordx4 v[124:127], v[84:85], off
	v_add_u32_e32 v84, 0xb0, v170
	v_mad_i64_i32 v[86:87], s[0:1], v84, s4, v[186:187]
	v_lshl_add_u64 v[96:97], v[86:87], 0, s[16:17]
	v_lshl_add_u64 v[86:87], v[96:97], 0, v[168:169]
	global_load_dwordx4 v[140:143], v[86:87], off nt
	v_ashrrev_i32_e32 v85, 31, v84
	v_lshlrev_b64 v[98:99], 12, v[84:85]
	v_lshl_add_u64 v[84:85], v[184:185], 0, v[98:99]
	global_load_dwordx4 v[84:87], v[84:85], off
	s_mov_b64 s[0:1], -1
	s_waitcnt vmcnt(3)
; #define GAS __attribute__((address_space(1)))
; __device__ __forceinline__ void unpack8(const v4u v, float (&f)[8]) { f[0] = bflo(v.x); f[1] = bfhi(v.x); f[2] = bflo(v.y); f[3] = bfhi(v.y); f[4] = bflo(v.z); f[5] = bfhi(v.z); f[6] = bflo(v.w); f[7] = bfhi(v.w); }
; __device__ __forceinline__ v4u pack8(const float (&f)[8]) { v4u o; o.x = cvt_pk_bf16(f[0], f[1]); o.y = cvt_pk_bf16(f[2], f[3]); o.z = cvt_pk_bf16(f[4], f[5]); o.w = cvt_pk_bf16(f[6], f[7]); return o; }
; __device__ __forceinline__ float sigmoidf_(float x) { return __builtin_amdgcn_rcpf(1.f + __expf(-x)); }
;     __device__ __forceinline__ void operator()(const f32x4 (&acc)[2][2][4][2], const pg8::Unit& u, int wr, int wc, int fr, int fq) const {
;     ...
;         for (int bj = 0; bj < 2; ++bj) { const int col = col0 + bj * 128;
;             const f32x4 b0 = *(const GAS f32x4*)(bgate + WHICH * DM + col), b1 = *(const GAS f32x4*)(bgate + WHICH * DM + col + 4);
; #pragma unroll
;             for (int aim = 0; aim < 4; ++aim) { const int ai = aim >> 1, mb = (aim & 1) * 2;
;                 v4u gv[4], tv[4];
; #pragma unroll
;                 for (int m = mb; m < mb + 2; ++m) { const int row = row0 + ai * 128 + m * 16;
;                     gv[m] = __builtin_nontemporal_load((const GAS v4u*)(proj + (size_t)row * NPROJ + OFF_GATE + WHICH * DM + col));
;                     if (WHICH == 1) tv[m] = *(const GAS v4u*)(ta + (size_t)row * DM + col); }
; #pragma unroll
;                 for (int m = mb; m < mb + 2; ++m) { const int row = row0 + ai * 128 + m * 16; float g[8]; unpack8(gv[m], g);
;                     const f32x4 a0 = acc[ai][bj][m][0], a1 = acc[ai][bj][m][1]; float r[8];
; #pragma unroll
;                     for (int e = 0; e < 4; ++e) { r[e] = sigmoidf_(g[e] + b0[e]) * a0[e]; r[4 + e] = sigmoidf_(g[4 + e] + b1[e]) * a1[e]; }
;                     if (WHICH == 0) *(GAS v4u*)(ta + (size_t)row * DM + col) = pack8(r);
;                     else { float tf[8]; unpack8(tv[m], tf);
; #pragma unroll
;                         for (int e = 0; e < 8; ++e) r[e] += tf[e];
;                         *(GAS v4u*)(mix + (size_t)row * DM + col) = pack8(r); } }
	v_lshlrev_b32_e32 v144, 16, v108
	v_and_b32_e32 v108, 0xffff0000, v108
	v_lshlrev_b32_e32 v145, 16, v109
	v_and_b32_e32 v109, 0xffff0000, v109
	v_lshlrev_b32_e32 v146, 16, v110
	v_fmamk_f32 v144, v144, 0xbfb8aa3b, v104
	v_fmamk_f32 v108, v108, 0xbfb8aa3b, v105
	v_and_b32_e32 v110, 0xffff0000, v110
	v_lshlrev_b32_e32 v147, 16, v111
	v_and_b32_e32 v111, 0xffff0000, v111
	v_fmamk_f32 v146, v146, 0xbfb8aa3b, v100
	v_fmamk_f32 v145, v145, 0xbfb8aa3b, v106
	v_fmamk_f32 v109, v109, 0xbfb8aa3b, v107
	v_exp_f32_e32 v144, v144
	v_exp_f32_e32 v108, v108
	v_fmamk_f32 v110, v110, 0xbfb8aa3b, v101
	v_fmamk_f32 v147, v147, 0xbfb8aa3b, v102
	v_fmamk_f32 v111, v111, 0xbfb8aa3b, v103
	v_exp_f32_e32 v146, v146
	v_exp_f32_e32 v145, v145
	v_exp_f32_e32 v109, v109
	v_exp_f32_e32 v110, v110
	v_exp_f32_e32 v147, v147
	v_exp_f32_e32 v111, v111
	v_add_f32_e32 v144, 1.0, v144
	v_add_f32_e32 v108, 1.0, v108
	v_rcp_f32_e32 v144, v144
	v_add_f32_e32 v146, 1.0, v146
	v_rcp_f32_e32 v108, v108
	v_add_f32_e32 v145, 1.0, v145
	v_add_f32_e32 v109, 1.0, v109
	v_rcp_f32_e32 v146, v146
	v_add_f32_e32 v110, 1.0, v110
	v_rcp_f32_e32 v145, v145
	v_add_f32_e32 v147, 1.0, v147
	v_rcp_f32_e32 v109, v109
	v_add_f32_e32 v111, 1.0, v111
	v_rcp_f32_e32 v110, v110
	v_rcp_f32_e32 v147, v147
	v_rcp_f32_e32 v111, v111
	s_waitcnt vmcnt(2)
	v_lshlrev_b32_e32 v159, 16, v124
	v_and_b32_e32 v124, 0xffff0000, v124
	v_lshlrev_b32_e32 v170, 16, v125
	v_and_b32_e32 v125, 0xffff0000, v125
	v_lshlrev_b32_e32 v171, 16, v126
	v_fmac_f32_e32 v159, v80, v144
	v_fmac_f32_e32 v124, v81, v108
	v_lshl_add_u64 v[80:81], s[46:47], 0, v[94:95]
	v_and_b32_e32 v126, 0xffff0000, v126
	v_lshlrev_b32_e32 v184, 16, v127
	v_and_b32_e32 v127, 0xffff0000, v127
	v_fmac_f32_e32 v170, v82, v145
	v_fmac_f32_e32 v125, v83, v109
	v_fmac_f32_e32 v171, v76, v146
	v_cvt_pk_bf16_f32 v76, v159, v124
	v_lshl_add_u64 v[82:83], v[80:81], 0, v[168:169]
	v_fmac_f32_e32 v126, v77, v110
	v_fmac_f32_e32 v184, v78, v147
	v_fmac_f32_e32 v127, v79, v111
	v_cvt_pk_bf16_f32 v77, v170, v125
	v_cvt_pk_bf16_f32 v78, v171, v126
	v_cvt_pk_bf16_f32 v79, v184, v127
	global_store_dwordx4 v[82:83], v[76:79], off
	s_waitcnt vmcnt(2)
	v_lshlrev_b32_e32 v80, 16, v142
	v_and_b32_e32 v81, 0xffff0000, v142
	v_lshlrev_b32_e32 v76, 16, v140
	v_and_b32_e32 v77, 0xffff0000, v140
	v_and_b32_e32 v79, 0xffff0000, v141
	v_fmamk_f32 v76, v76, 0xbfb8aa3b, v104
	v_lshlrev_b32_e32 v78, 16, v141
	v_fmamk_f32 v77, v77, 0xbfb8aa3b, v105
	v_fmamk_f32 v79, v79, 0xbfb8aa3b, v107
	v_lshlrev_b32_e32 v108, 16, v143
	v_and_b32_e32 v109, 0xffff0000, v143
	v_exp_f32_e32 v76, v76
	v_fmamk_f32 v80, v80, 0xbfb8aa3b, v100
	v_fmamk_f32 v81, v81, 0xbfb8aa3b, v101
	v_fmamk_f32 v78, v78, 0xbfb8aa3b, v106
	v_exp_f32_e32 v77, v77
	v_fmamk_f32 v100, v108, 0xbfb8aa3b, v102
	v_exp_f32_e32 v79, v79
	v_fmamk_f32 v101, v109, 0xbfb8aa3b, v103
	v_exp_f32_e32 v80, v80
	v_exp_f32_e32 v81, v81
	v_exp_f32_e32 v78, v78
	v_exp_f32_e32 v100, v100
	v_exp_f32_e32 v101, v101
	v_add_f32_e32 v76, 1.0, v76
	v_rcp_f32_e32 v76, v76
	v_add_f32_e32 v77, 1.0, v77
	v_add_f32_e32 v79, 1.0, v79
	v_add_f32_e32 v80, 1.0, v80
	v_rcp_f32_e32 v77, v77
	v_add_f32_e32 v81, 1.0, v81
	v_add_f32_e32 v78, 1.0, v78
	v_rcp_f32_e32 v79, v79
	v_rcp_f32_e32 v80, v80
	v_rcp_f32_e32 v81, v81
	v_rcp_f32_e32 v78, v78
	v_add_f32_e32 v100, 1.0, v100
	v_add_f32_e32 v101, 1.0, v101
	v_rcp_f32_e32 v100, v100
	v_rcp_f32_e32 v101, v101
	s_waitcnt vmcnt(1)
	v_lshlrev_b32_e32 v102, 16, v84
	v_and_b32_e32 v84, 0xffff0000, v84
	v_lshlrev_b32_e32 v103, 16, v85
	v_and_b32_e32 v85, 0xffff0000, v85
	v_fmac_f32_e32 v102, v72, v76
	v_or_b32_e32 v76, 0x80, v158
	v_lshlrev_b32_e32 v104, 16, v86
	v_and_b32_e32 v86, 0xffff0000, v86
	v_fmac_f32_e32 v84, v73, v77
	v_fmac_f32_e32 v85, v75, v79
	v_lshl_add_u64 v[72:73], s[46:47], 0, v[98:99]
	v_ashrrev_i32_e32 v77, 31, v76
	v_lshlrev_b32_e32 v105, 16, v87
	v_and_b32_e32 v87, 0xffff0000, v87
	v_fmac_f32_e32 v103, v74, v78
	v_fmac_f32_e32 v104, v68, v80
	v_fmac_f32_e32 v86, v69, v81
	v_cvt_pk_bf16_f32 v68, v102, v84
	v_cvt_pk_bf16_f32 v69, v103, v85
	v_lshl_add_u64 v[80:81], v[72:73], 0, v[168:169]
	v_lshlrev_b64 v[84:85], 1, v[76:77]
	v_fmac_f32_e32 v105, v70, v100
	v_fmac_f32_e32 v87, v71, v101
	v_cvt_pk_bf16_f32 v70, v104, v86
	v_cvt_pk_bf16_f32 v71, v105, v87
	global_store_dwordx4 v[80:81], v[68:71], off
	v_lshl_add_u64 v[72:73], v[76:77], 2, s[14:15]
	v_lshl_add_u64 v[76:77], v[162:163], 0, v[84:85]
	global_load_dwordx4 v[68:71], v[72:73], off offset:16
	s_nop 0
	global_load_dwordx4 v[72:75], v[72:73], off
	s_nop 0
	global_load_dwordx4 v[100:103], v[76:77], off nt
	v_lshl_add_u64 v[76:77], s[44:45], 0, v[160:161]
	v_lshl_add_u64 v[76:77], v[76:77], 0, v[84:85]
	global_load_dwordx4 v[104:107], v[76:77], off
	v_lshl_add_u64 v[76:77], v[164:165], 0, v[84:85]
	global_load_dwordx4 v[108:111], v[76:77], off nt
	v_lshl_add_u64 v[76:77], s[44:45], 0, v[166:167]
	v_lshl_add_u64 v[76:77], v[76:77], 0, v[84:85]
	global_load_dwordx4 v[76:79], v[76:77], off
	s_waitcnt vmcnt(3)
; #define GAS __attribute__((address_space(1)))
; __device__ __forceinline__ void unpack8(const v4u v, float (&f)[8]) { f[0] = bflo(v.x); f[1] = bfhi(v.x); f[2] = bflo(v.y); f[3] = bfhi(v.y); f[4] = bflo(v.z); f[5] = bfhi(v.z); f[6] = bflo(v.w); f[7] = bfhi(v.w); }
; __device__ __forceinline__ v4u pack8(const float (&f)[8]) { v4u o; o.x = cvt_pk_bf16(f[0], f[1]); o.y = cvt_pk_bf16(f[2], f[3]); o.z = cvt_pk_bf16(f[4], f[5]); o.w = cvt_pk_bf16(f[6], f[7]); return o; }
; __device__ __forceinline__ float sigmoidf_(float x) { return __builtin_amdgcn_rcpf(1.f + __expf(-x)); }
;     __device__ __forceinline__ void operator()(const f32x4 (&acc)[2][2][4][2], const pg8::Unit& u, int wr, int wc, int fr, int fq) const {
;     ...
;         for (int bj = 0; bj < 2; ++bj) { const int col = col0 + bj * 128;
;             const f32x4 b0 = *(const GAS f32x4*)(bgate + WHICH * DM + col), b1 = *(const GAS f32x4*)(bgate + WHICH * DM + col + 4);
; #pragma unroll
;             for (int aim = 0; aim < 4; ++aim) { const int ai = aim >> 1, mb = (aim & 1) * 2;
;                 v4u gv[4], tv[4];
; #pragma unroll
;                 for (int m = mb; m < mb + 2; ++m) { const int row = row0 + ai * 128 + m * 16;
;                     gv[m] = __builtin_nontemporal_load((const GAS v4u*)(proj + (size_t)row * NPROJ + OFF_GATE + WHICH * DM + col));
;                     if (WHICH == 1) tv[m] = *(const GAS v4u*)(ta + (size_t)row * DM + col); }
; #pragma unroll
;                 for (int m = mb; m < mb + 2; ++m) { const int row = row0 + ai * 128 + m * 16; float g[8]; unpack8(gv[m], g);
;                     const f32x4 a0 = acc[ai][bj][m][0], a1 = acc[ai][bj][m][1]; float r[8];
; #pragma unroll
;                     for (int e = 0; e < 4; ++e) { r[e] = sigmoidf_(g[e] + b0[e]) * a0[e]; r[4 + e] = sigmoidf_(g[4 + e] + b1[e]) * a1[e]; }
;                     if (WHICH == 0) *(GAS v4u*)(ta + (size_t)row * DM + col) = pack8(r);
;                     else { float tf[8]; unpack8(tv[m], tf);
; #pragma unroll
;                         for (int e = 0; e < 8; ++e) r[e] += tf[e];
;                         *(GAS v4u*)(mix + (size_t)row * DM + col) = pack8(r); } }
	v_lshlrev_b32_e32 v86, 16, v100
	v_and_b32_e32 v87, 0xffff0000, v100
	v_lshlrev_b32_e32 v100, 16, v101
	v_and_b32_e32 v101, 0xffff0000, v101
	v_lshlrev_b32_e32 v124, 16, v102
	v_and_b32_e32 v102, 0xffff0000, v102
	v_lshlrev_b32_e32 v125, 16, v103
	v_and_b32_e32 v103, 0xffff0000, v103
	v_mul_f32_e32 v72, 0xbfb8aa3b, v72
	v_fmamk_f32 v86, v86, 0xbfb8aa3b, v72
	v_mul_f32_e32 v68, 0xbfb8aa3b, v68
	v_fmamk_f32 v124, v124, 0xbfb8aa3b, v68
	v_mul_f32_e32 v73, 0xbfb8aa3b, v73
	v_fmamk_f32 v87, v87, 0xbfb8aa3b, v73
	v_mul_f32_e32 v69, 0xbfb8aa3b, v69
	v_fmamk_f32 v102, v102, 0xbfb8aa3b, v69
	v_mul_f32_e32 v74, 0xbfb8aa3b, v74
	v_fmamk_f32 v100, v100, 0xbfb8aa3b, v74
	v_mul_f32_e32 v70, 0xbfb8aa3b, v70
	v_fmamk_f32 v125, v125, 0xbfb8aa3b, v70
	v_mul_f32_e32 v75, 0xbfb8aa3b, v75
	v_fmamk_f32 v101, v101, 0xbfb8aa3b, v75
	v_mul_f32_e32 v71, 0xbfb8aa3b, v71
	v_fmamk_f32 v103, v103, 0xbfb8aa3b, v71
	v_exp_f32_e32 v86, v86
	v_exp_f32_e32 v124, v124
	v_exp_f32_e32 v87, v87
	v_exp_f32_e32 v102, v102
	v_exp_f32_e32 v100, v100
	v_exp_f32_e32 v125, v125
	v_exp_f32_e32 v101, v101
	v_exp_f32_e32 v103, v103
	v_add_f32_e32 v86, 1.0, v86
	v_add_f32_e32 v124, 1.0, v124
	v_add_f32_e32 v87, 1.0, v87
	v_add_f32_e32 v102, 1.0, v102
	v_add_f32_e32 v100, 1.0, v100
	v_add_f32_e32 v125, 1.0, v125
	v_add_f32_e32 v101, 1.0, v101
	v_add_f32_e32 v103, 1.0, v103
	v_rcp_f32_e32 v86, v86
	v_rcp_f32_e32 v124, v124
	v_rcp_f32_e32 v87, v87
	v_rcp_f32_e32 v102, v102
	v_rcp_f32_e32 v100, v100
	v_rcp_f32_e32 v125, v125
	v_rcp_f32_e32 v101, v101
	v_rcp_f32_e32 v103, v103
	s_waitcnt vmcnt(2)
	v_lshlrev_b32_e32 v126, 16, v104
	v_and_b32_e32 v104, 0xffff0000, v104
	v_lshlrev_b32_e32 v127, 16, v105
	v_and_b32_e32 v105, 0xffff0000, v105
	v_lshlrev_b32_e32 v140, 16, v106
	v_and_b32_e32 v106, 0xffff0000, v106
	v_lshlrev_b32_e32 v141, 16, v107
	v_and_b32_e32 v107, 0xffff0000, v107
	v_fmac_f32_e32 v126, v64, v86
	v_fmac_f32_e32 v104, v65, v87
	v_fmac_f32_e32 v127, v66, v100
	v_fmac_f32_e32 v105, v67, v101
	v_fmac_f32_e32 v140, v60, v124
	v_fmac_f32_e32 v106, v61, v102
	v_fmac_f32_e32 v141, v62, v125
	v_fmac_f32_e32 v107, v63, v103
	v_cvt_pk_bf16_f32 v60, v126, v104
	v_cvt_pk_bf16_f32 v61, v127, v105
	v_cvt_pk_bf16_f32 v62, v140, v106
	v_cvt_pk_bf16_f32 v63, v141, v107
	global_store_dwordx4 v[136:137], v[60:63], off offset:256
	s_waitcnt vmcnt(2)
	v_lshlrev_b32_e32 v64, 16, v110
	v_and_b32_e32 v65, 0xffff0000, v110
	v_lshlrev_b32_e32 v60, 16, v108
	v_and_b32_e32 v61, 0xffff0000, v108
	v_lshlrev_b32_e32 v62, 16, v109
	v_and_b32_e32 v63, 0xffff0000, v109
	v_lshlrev_b32_e32 v66, 16, v111
	v_and_b32_e32 v67, 0xffff0000, v111
	v_fmamk_f32 v60, v60, 0xbfb8aa3b, v72
	v_fmamk_f32 v64, v64, 0xbfb8aa3b, v68
	v_fmamk_f32 v61, v61, 0xbfb8aa3b, v73
	v_fmamk_f32 v65, v65, 0xbfb8aa3b, v69
	v_fmamk_f32 v62, v62, 0xbfb8aa3b, v74
	v_fmamk_f32 v63, v63, 0xbfb8aa3b, v75
	v_fmamk_f32 v66, v66, 0xbfb8aa3b, v70
	v_fmamk_f32 v67, v67, 0xbfb8aa3b, v71
	v_exp_f32_e32 v60, v60
	v_exp_f32_e32 v64, v64
	v_exp_f32_e32 v61, v61
	v_exp_f32_e32 v65, v65
	v_exp_f32_e32 v62, v62
	v_exp_f32_e32 v63, v63
	v_exp_f32_e32 v66, v66
	v_exp_f32_e32 v67, v67
	v_add_f32_e32 v60, 1.0, v60
	v_add_f32_e32 v64, 1.0, v64
	v_add_f32_e32 v61, 1.0, v61
	v_add_f32_e32 v65, 1.0, v65
	v_add_f32_e32 v62, 1.0, v62
	v_add_f32_e32 v63, 1.0, v63
	v_rcp_f32_e32 v60, v60
	v_rcp_f32_e32 v64, v64
	v_rcp_f32_e32 v61, v61
	v_rcp_f32_e32 v65, v65
	v_rcp_f32_e32 v62, v62
	v_add_f32_e32 v66, 1.0, v66
	v_rcp_f32_e32 v63, v63
	v_add_f32_e32 v67, 1.0, v67
	v_rcp_f32_e32 v66, v66
	v_rcp_f32_e32 v67, v67
	s_waitcnt vmcnt(1)
	v_lshlrev_b32_e32 v86, 16, v76
	v_and_b32_e32 v76, 0xffff0000, v76
	v_lshlrev_b32_e32 v87, 16, v77
	v_and_b32_e32 v77, 0xffff0000, v77
	v_lshlrev_b32_e32 v100, 16, v78
	v_and_b32_e32 v78, 0xffff0000, v78
	v_lshlrev_b32_e32 v101, 16, v79
	v_and_b32_e32 v79, 0xffff0000, v79
	v_fmac_f32_e32 v86, v56, v60
	v_fmac_f32_e32 v76, v57, v61
	v_fmac_f32_e32 v87, v58, v62
	v_fmac_f32_e32 v77, v59, v63
	v_fmac_f32_e32 v100, v52, v64
	v_fmac_f32_e32 v78, v53, v65
	v_cvt_pk_bf16_f32 v52, v86, v76
	v_cvt_pk_bf16_f32 v53, v87, v77
	v_fmac_f32_e32 v101, v54, v66
	v_fmac_f32_e32 v79, v55, v67
	v_cvt_pk_bf16_f32 v54, v100, v78
	v_cvt_pk_bf16_f32 v55, v101, v79
	global_store_dwordx4 v[128:129], v[52:55], off offset:256
	s_nop 1
	v_lshl_add_u64 v[52:53], v[130:131], 0, v[84:85]
	global_load_dwordx4 v[56:59], v[52:53], off nt
	v_lshl_add_u64 v[52:53], s[44:45], 0, v[132:133]
	v_lshl_add_u64 v[52:53], v[52:53], 0, v[84:85]
	global_load_dwordx4 v[60:63], v[52:53], off
	v_lshl_add_u64 v[52:53], v[134:135], 0, v[84:85]
	global_load_dwordx4 v[64:67], v[52:53], off nt
	v_lshl_add_u64 v[52:53], s[44:45], 0, v[138:139]
	v_lshl_add_u64 v[52:53], v[52:53], 0, v[84:85]
	global_load_dwordx4 v[52:55], v[52:53], off
	s_waitcnt vmcnt(3)
	v_lshlrev_b32_e32 v76, 16, v56
	v_and_b32_e32 v56, 0xffff0000, v56
	v_lshlrev_b32_e32 v77, 16, v57
	v_and_b32_e32 v57, 0xffff0000, v57
	v_lshlrev_b32_e32 v78, 16, v58
	v_and_b32_e32 v58, 0xffff0000, v58
	v_lshlrev_b32_e32 v79, 16, v59
	v_and_b32_e32 v59, 0xffff0000, v59
	v_fmamk_f32 v76, v76, 0xbfb8aa3b, v72
	v_fmamk_f32 v78, v78, 0xbfb8aa3b, v68
	v_fmamk_f32 v56, v56, 0xbfb8aa3b, v73
	v_fmamk_f32 v58, v58, 0xbfb8aa3b, v69
	v_fmamk_f32 v77, v77, 0xbfb8aa3b, v74
	v_fmamk_f32 v79, v79, 0xbfb8aa3b, v70
	v_fmamk_f32 v57, v57, 0xbfb8aa3b, v75
	v_fmamk_f32 v59, v59, 0xbfb8aa3b, v71
	v_exp_f32_e32 v76, v76
	v_exp_f32_e32 v78, v78
	v_exp_f32_e32 v56, v56
	v_exp_f32_e32 v58, v58
	v_exp_f32_e32 v77, v77
	v_exp_f32_e32 v79, v79
	v_exp_f32_e32 v57, v57
	v_exp_f32_e32 v59, v59
	v_add_f32_e32 v76, 1.0, v76
	v_add_f32_e32 v78, 1.0, v78
	v_add_f32_e32 v56, 1.0, v56
	v_add_f32_e32 v58, 1.0, v58
	v_add_f32_e32 v77, 1.0, v77
	v_add_f32_e32 v79, 1.0, v79
	v_add_f32_e32 v57, 1.0, v57
	v_add_f32_e32 v59, 1.0, v59
	v_rcp_f32_e32 v76, v76
	v_rcp_f32_e32 v78, v78
	v_rcp_f32_e32 v56, v56
	v_rcp_f32_e32 v58, v58
	v_rcp_f32_e32 v77, v77
	v_rcp_f32_e32 v79, v79
	v_rcp_f32_e32 v57, v57
	v_rcp_f32_e32 v59, v59
	s_waitcnt vmcnt(2)
; #define GAS __attribute__((address_space(1)))
; __device__ __forceinline__ void unpack8(const v4u v, float (&f)[8]) { f[0] = bflo(v.x); f[1] = bfhi(v.x); f[2] = bflo(v.y); f[3] = bfhi(v.y); f[4] = bflo(v.z); f[5] = bfhi(v.z); f[6] = bflo(v.w); f[7] = bfhi(v.w); }
; __device__ __forceinline__ v4u pack8(const float (&f)[8]) { v4u o; o.x = cvt_pk_bf16(f[0], f[1]); o.y = cvt_pk_bf16(f[2], f[3]); o.z = cvt_pk_bf16(f[4], f[5]); o.w = cvt_pk_bf16(f[6], f[7]); return o; }
; __device__ __forceinline__ float sigmoidf_(float x) { return __builtin_amdgcn_rcpf(1.f + __expf(-x)); }
;     __device__ __forceinline__ void operator()(const f32x4 (&acc)[2][2][4][2], const pg8::Unit& u, int wr, int wc, int fr, int fq) const {
;     ...
;         for (int bj = 0; bj < 2; ++bj) { const int col = col0 + bj * 128;
;             const f32x4 b0 = *(const GAS f32x4*)(bgate + WHICH * DM + col), b1 = *(const GAS f32x4*)(bgate + WHICH * DM + col + 4);
; #pragma unroll
;             for (int aim = 0; aim < 4; ++aim) { const int ai = aim >> 1, mb = (aim & 1) * 2;
;                 v4u gv[4], tv[4];
; #pragma unroll
;                 for (int m = mb; m < mb + 2; ++m) { const int row = row0 + ai * 128 + m * 16;
;                     gv[m] = __builtin_nontemporal_load((const GAS v4u*)(proj + (size_t)row * NPROJ + OFF_GATE + WHICH * DM + col));
;                     if (WHICH == 1) tv[m] = *(const GAS v4u*)(ta + (size_t)row * DM + col); }
; #pragma unroll
;                 for (int m = mb; m < mb + 2; ++m) { const int row = row0 + ai * 128 + m * 16; float g[8]; unpack8(gv[m], g);
;                     const f32x4 a0 = acc[ai][bj][m][0], a1 = acc[ai][bj][m][1]; float r[8];
; #pragma unroll
;                     for (int e = 0; e < 4; ++e) { r[e] = sigmoidf_(g[e] + b0[e]) * a0[e]; r[4 + e] = sigmoidf_(g[4 + e] + b1[e]) * a1[e]; }
;                     if (WHICH == 0) *(GAS v4u*)(ta + (size_t)row * DM + col) = pack8(r);
;                     else { float tf[8]; unpack8(tv[m], tf);
; #pragma unroll
;                         for (int e = 0; e < 8; ++e) r[e] += tf[e];
;                         *(GAS v4u*)(mix + (size_t)row * DM + col) = pack8(r); } }
	v_lshlrev_b32_e32 v86, 16, v60
	v_and_b32_e32 v60, 0xffff0000, v60
	v_lshlrev_b32_e32 v87, 16, v61
	v_and_b32_e32 v61, 0xffff0000, v61
	v_lshlrev_b32_e32 v100, 16, v62
	v_and_b32_e32 v62, 0xffff0000, v62
	v_lshlrev_b32_e32 v101, 16, v63
	v_and_b32_e32 v63, 0xffff0000, v63
	v_fmac_f32_e32 v86, v48, v76
	v_fmac_f32_e32 v60, v49, v56
	v_fmac_f32_e32 v87, v50, v77
	v_fmac_f32_e32 v61, v51, v57
	v_fmac_f32_e32 v100, v44, v78
	v_fmac_f32_e32 v62, v45, v58
	v_fmac_f32_e32 v101, v46, v79
	v_fmac_f32_e32 v63, v47, v59
	v_cvt_pk_bf16_f32 v44, v86, v60
	v_cvt_pk_bf16_f32 v45, v87, v61
	v_cvt_pk_bf16_f32 v46, v100, v62
	v_cvt_pk_bf16_f32 v47, v101, v63
	global_store_dwordx4 v[116:117], v[44:47], off offset:256
	s_waitcnt vmcnt(2)
	v_lshlrev_b32_e32 v48, 16, v66
	v_and_b32_e32 v49, 0xffff0000, v66
	v_lshlrev_b32_e32 v44, 16, v64
	v_and_b32_e32 v45, 0xffff0000, v64
	v_lshlrev_b32_e32 v46, 16, v65
	v_and_b32_e32 v47, 0xffff0000, v65
	v_lshlrev_b32_e32 v50, 16, v67
	v_and_b32_e32 v51, 0xffff0000, v67
	v_fmamk_f32 v44, v44, 0xbfb8aa3b, v72
	v_fmamk_f32 v48, v48, 0xbfb8aa3b, v68
	v_fmamk_f32 v45, v45, 0xbfb8aa3b, v73
	v_fmamk_f32 v49, v49, 0xbfb8aa3b, v69
	v_fmamk_f32 v46, v46, 0xbfb8aa3b, v74
	v_fmamk_f32 v47, v47, 0xbfb8aa3b, v75
	v_fmamk_f32 v50, v50, 0xbfb8aa3b, v70
	v_fmamk_f32 v51, v51, 0xbfb8aa3b, v71
	v_exp_f32_e32 v44, v44
	v_exp_f32_e32 v48, v48
	v_exp_f32_e32 v45, v45
	v_exp_f32_e32 v49, v49
	v_exp_f32_e32 v46, v46
	v_exp_f32_e32 v47, v47
	v_exp_f32_e32 v50, v50
	v_exp_f32_e32 v51, v51
	v_add_f32_e32 v44, 1.0, v44
	v_add_f32_e32 v48, 1.0, v48
	v_add_f32_e32 v45, 1.0, v45
	v_add_f32_e32 v49, 1.0, v49
	v_add_f32_e32 v46, 1.0, v46
	v_add_f32_e32 v47, 1.0, v47
	v_rcp_f32_e32 v44, v44
	v_rcp_f32_e32 v48, v48
	v_rcp_f32_e32 v45, v45
	v_rcp_f32_e32 v49, v49
	v_rcp_f32_e32 v46, v46
	v_add_f32_e32 v50, 1.0, v50
	v_rcp_f32_e32 v47, v47
	v_add_f32_e32 v51, 1.0, v51
	v_rcp_f32_e32 v50, v50
	v_rcp_f32_e32 v51, v51
	s_waitcnt vmcnt(1)
	v_lshlrev_b32_e32 v56, 16, v52
	v_and_b32_e32 v52, 0xffff0000, v52
	v_lshlrev_b32_e32 v57, 16, v53
	v_and_b32_e32 v53, 0xffff0000, v53
	v_lshlrev_b32_e32 v58, 16, v54
	v_and_b32_e32 v54, 0xffff0000, v54
	v_lshlrev_b32_e32 v59, 16, v55
	v_and_b32_e32 v55, 0xffff0000, v55
	v_fmac_f32_e32 v56, v40, v44
	v_fmac_f32_e32 v52, v41, v45
	v_fmac_f32_e32 v57, v42, v46
	v_fmac_f32_e32 v53, v43, v47
	v_fmac_f32_e32 v58, v36, v48
	v_fmac_f32_e32 v54, v37, v49
	v_cvt_pk_bf16_f32 v36, v56, v52
	v_cvt_pk_bf16_f32 v37, v57, v53
	v_fmac_f32_e32 v59, v38, v50
	v_fmac_f32_e32 v55, v39, v51
	v_cvt_pk_bf16_f32 v38, v58, v54
	v_cvt_pk_bf16_f32 v39, v59, v55
	global_store_dwordx4 v[112:113], v[36:39], off offset:256
	s_nop 1
	v_lshl_add_u64 v[36:37], v[114:115], 0, v[84:85]
	global_load_dwordx4 v[40:43], v[36:37], off nt
	v_lshl_add_u64 v[36:37], s[44:45], 0, v[118:119]
	v_lshl_add_u64 v[36:37], v[36:37], 0, v[84:85]
	global_load_dwordx4 v[44:47], v[36:37], off
	v_lshl_add_u64 v[36:37], v[120:121], 0, v[84:85]
	global_load_dwordx4 v[48:51], v[36:37], off nt
	v_lshl_add_u64 v[36:37], s[44:45], 0, v[122:123]
	v_lshl_add_u64 v[36:37], v[36:37], 0, v[84:85]
	global_load_dwordx4 v[36:39], v[36:37], off
	s_waitcnt vmcnt(3)
	v_lshlrev_b32_e32 v52, 16, v40
	v_and_b32_e32 v40, 0xffff0000, v40
	v_lshlrev_b32_e32 v53, 16, v41
	v_and_b32_e32 v41, 0xffff0000, v41
	v_lshlrev_b32_e32 v54, 16, v42
	v_and_b32_e32 v42, 0xffff0000, v42
	v_lshlrev_b32_e32 v55, 16, v43
	v_and_b32_e32 v43, 0xffff0000, v43
	v_fmamk_f32 v52, v52, 0xbfb8aa3b, v72
	v_fmamk_f32 v54, v54, 0xbfb8aa3b, v68
	v_fmamk_f32 v40, v40, 0xbfb8aa3b, v73
	v_fmamk_f32 v42, v42, 0xbfb8aa3b, v69
	v_fmamk_f32 v53, v53, 0xbfb8aa3b, v74
	v_fmamk_f32 v55, v55, 0xbfb8aa3b, v70
	v_fmamk_f32 v41, v41, 0xbfb8aa3b, v75
	v_fmamk_f32 v43, v43, 0xbfb8aa3b, v71
	v_exp_f32_e32 v52, v52
	v_exp_f32_e32 v54, v54
	v_exp_f32_e32 v40, v40
	v_exp_f32_e32 v42, v42
	v_exp_f32_e32 v53, v53
	v_exp_f32_e32 v55, v55
	v_exp_f32_e32 v41, v41
	v_exp_f32_e32 v43, v43
	v_add_f32_e32 v52, 1.0, v52
	v_add_f32_e32 v54, 1.0, v54
	v_add_f32_e32 v40, 1.0, v40
	v_add_f32_e32 v42, 1.0, v42
	v_add_f32_e32 v53, 1.0, v53
	v_add_f32_e32 v55, 1.0, v55
	v_add_f32_e32 v41, 1.0, v41
	v_add_f32_e32 v43, 1.0, v43
	v_rcp_f32_e32 v52, v52
	v_rcp_f32_e32 v54, v54
	v_rcp_f32_e32 v40, v40
	v_rcp_f32_e32 v42, v42
	v_rcp_f32_e32 v53, v53
	v_rcp_f32_e32 v55, v55
	v_rcp_f32_e32 v41, v41
	v_rcp_f32_e32 v43, v43
	s_waitcnt vmcnt(2)
	v_lshlrev_b32_e32 v56, 16, v44
	v_and_b32_e32 v44, 0xffff0000, v44
	v_lshlrev_b32_e32 v57, 16, v45
	v_and_b32_e32 v45, 0xffff0000, v45
	v_lshlrev_b32_e32 v58, 16, v46
	v_and_b32_e32 v46, 0xffff0000, v46
	v_lshlrev_b32_e32 v59, 16, v47
	v_and_b32_e32 v47, 0xffff0000, v47
	v_fmac_f32_e32 v56, v32, v52
	v_fmac_f32_e32 v44, v33, v40
	v_fmac_f32_e32 v57, v34, v53
	v_fmac_f32_e32 v45, v35, v41
	v_fmac_f32_e32 v58, v28, v54
	v_fmac_f32_e32 v46, v29, v42
	v_fmac_f32_e32 v59, v30, v55
	v_fmac_f32_e32 v47, v31, v43
	v_cvt_pk_bf16_f32 v28, v56, v44
	v_cvt_pk_bf16_f32 v29, v57, v45
	v_cvt_pk_bf16_f32 v30, v58, v46
	v_cvt_pk_bf16_f32 v31, v59, v47
	global_store_dwordx4 v[92:93], v[28:31], off offset:256
	s_waitcnt vmcnt(2)
; #define PG8_BAR __builtin_amdgcn_s_barrier()
; template <class Epi, class Sched, bool ALIGN_EPI = false, bool SP2 = false>
; __device__ __forceinline__ void gemm_phase(PG8_LAS unsigned char* lds, const Gemm g, const Sched& S, const Epi& E) {
;     ...
;         if constexpr (ALIGN_EPI) { if (wr == 0) PG8_BAR; }
;         if constexpr (!Epi::AFTER_DRAIN) { E(acc, cur, wr, wc, fr, fq); S.done(cur); }
;         if (!has_next) break;
; #pragma unroll
;         for (int a = 0; a < 2; ++a)
; #pragma unroll
;             for (int b = 0; b < 2; ++b)
; #pragma unroll
;                 for (int m = 0; m < 4; ++m)
; #pragma unroll
;                     for (int n = 0; n < 2; ++n) acc[a][b][m][n] = (f32x4){0.f, 0.f, 0.f, 0.f};
;         cur = nxt; cA = nA; cB = nB; ++ui;
;         if constexpr (ALIGN_EPI) { if (wr == 1) PG8_BAR; }
;     __device__ __forceinline__ void operator()(const f32x4 (&acc)[2][2][4][2], const pg8::Unit& u, int wr, int wc, int fr, int fq) const {
;     ...
;         for (int bj = 0; bj < 2; ++bj) { const int col = col0 + bj * 128;
;             const f32x4 b0 = *(const GAS f32x4*)(bgate + WHICH * DM + col), b1 = *(const GAS f32x4*)(bgate + WHICH * DM + col + 4);
; #pragma unroll
;             for (int aim = 0; aim < 4; ++aim) { const int ai = aim >> 1, mb = (aim & 1) * 2;
;                 v4u gv[4], tv[4];
; #pragma unroll
;                 for (int m = mb; m < mb + 2; ++m) { const int row = row0 + ai * 128 + m * 16;
;                     gv[m] = __builtin_nontemporal_load((const GAS v4u*)(proj + (size_t)row * NPROJ + OFF_GATE + WHICH * DM + col));
;                     if (WHICH == 1) tv[m] = *(const GAS v4u*)(ta + (size_t)row * DM + col); }
; #pragma unroll
;                 for (int m = mb; m < mb + 2; ++m) { const int row = row0 + ai * 128 + m * 16; float g[8]; unpack8(gv[m], g);
;                     const f32x4 a0 = acc[ai][bj][m][0], a1 = acc[ai][bj][m][1]; float r[8];
; #pragma unroll
;                     for (int e = 0; e < 4; ++e) { r[e] = sigmoidf_(g[e] + b0[e]) * a0[e]; r[4 + e] = sigmoidf_(g[4 + e] + b1[e]) * a1[e]; }
;                     if (WHICH == 0) *(GAS v4u*)(ta + (size_t)row * DM + col) = pack8(r);
;                     else { float tf[8]; unpack8(tv[m], tf);
; #pragma unroll
;                         for (int e = 0; e < 8; ++e) r[e] += tf[e];
;                         *(GAS v4u*)(mix + (size_t)row * DM + col) = pack8(r); } }
	v_lshlrev_b32_e32 v32, 16, v50
	v_and_b32_e32 v33, 0xffff0000, v50
	v_lshlrev_b32_e32 v28, 16, v48
	v_and_b32_e32 v29, 0xffff0000, v48
	v_lshlrev_b32_e32 v30, 16, v49
	v_and_b32_e32 v31, 0xffff0000, v49
	v_lshlrev_b32_e32 v34, 16, v51
	v_and_b32_e32 v35, 0xffff0000, v51
	v_fmamk_f32 v28, v28, 0xbfb8aa3b, v72
	v_fmamk_f32 v32, v32, 0xbfb8aa3b, v68
	v_fmamk_f32 v29, v29, 0xbfb8aa3b, v73
	v_fmamk_f32 v33, v33, 0xbfb8aa3b, v69
	v_fmamk_f32 v30, v30, 0xbfb8aa3b, v74
	v_fmamk_f32 v31, v31, 0xbfb8aa3b, v75
	v_fmamk_f32 v34, v34, 0xbfb8aa3b, v70
	v_fmamk_f32 v35, v35, 0xbfb8aa3b, v71
	v_exp_f32_e32 v28, v28
	v_exp_f32_e32 v32, v32
	v_exp_f32_e32 v29, v29
	v_exp_f32_e32 v33, v33
	v_exp_f32_e32 v30, v30
	v_exp_f32_e32 v31, v31
	v_exp_f32_e32 v34, v34
	v_exp_f32_e32 v35, v35
	v_add_f32_e32 v28, 1.0, v28
	v_add_f32_e32 v32, 1.0, v32
	v_add_f32_e32 v29, 1.0, v29
	v_add_f32_e32 v33, 1.0, v33
	v_add_f32_e32 v30, 1.0, v30
	v_add_f32_e32 v31, 1.0, v31
	v_rcp_f32_e32 v28, v28
	v_rcp_f32_e32 v32, v32
	v_rcp_f32_e32 v29, v29
	v_rcp_f32_e32 v33, v33
	v_rcp_f32_e32 v30, v30
	v_add_f32_e32 v34, 1.0, v34
	v_rcp_f32_e32 v31, v31
	v_add_f32_e32 v35, 1.0, v35
	v_rcp_f32_e32 v34, v34
	v_rcp_f32_e32 v35, v35
	s_waitcnt vmcnt(1)
	v_lshlrev_b32_e32 v40, 16, v36
	v_and_b32_e32 v36, 0xffff0000, v36
	v_lshlrev_b32_e32 v41, 16, v37
	v_and_b32_e32 v37, 0xffff0000, v37
	v_lshlrev_b32_e32 v42, 16, v38
	v_and_b32_e32 v38, 0xffff0000, v38
	v_lshlrev_b32_e32 v43, 16, v39
	v_and_b32_e32 v39, 0xffff0000, v39
	v_fmac_f32_e32 v40, v24, v28
	v_fmac_f32_e32 v36, v25, v29
	v_fmac_f32_e32 v41, v26, v30
	v_fmac_f32_e32 v37, v27, v31
	v_fmac_f32_e32 v42, v20, v32
	v_fmac_f32_e32 v38, v21, v33
	v_cvt_pk_bf16_f32 v20, v40, v36
	v_cvt_pk_bf16_f32 v21, v41, v37
	v_fmac_f32_e32 v43, v22, v34
	v_fmac_f32_e32 v39, v23, v35
	v_cvt_pk_bf16_f32 v22, v42, v38
	v_cvt_pk_bf16_f32 v23, v43, v39
	global_store_dwordx4 v[88:89], v[20:23], off offset:256
	s_nop 1
	v_lshl_add_u64 v[20:21], v[90:91], 0, v[84:85]
	global_load_dwordx4 v[24:27], v[20:21], off nt
	v_lshl_add_u64 v[20:21], s[44:45], 0, v[94:95]
	v_lshl_add_u64 v[20:21], v[20:21], 0, v[84:85]
	global_load_dwordx4 v[28:31], v[20:21], off
	v_lshl_add_u64 v[20:21], v[96:97], 0, v[84:85]
	global_load_dwordx4 v[32:35], v[20:21], off nt
	v_lshl_add_u64 v[20:21], s[44:45], 0, v[98:99]
	v_lshl_add_u64 v[20:21], v[20:21], 0, v[84:85]
	global_load_dwordx4 v[20:23], v[20:21], off
	s_waitcnt vmcnt(3)
	v_lshlrev_b32_e32 v36, 16, v24
	v_and_b32_e32 v24, 0xffff0000, v24
	v_lshlrev_b32_e32 v37, 16, v25
	v_and_b32_e32 v25, 0xffff0000, v25
	v_lshlrev_b32_e32 v38, 16, v26
	v_and_b32_e32 v26, 0xffff0000, v26
	v_lshlrev_b32_e32 v39, 16, v27
	v_and_b32_e32 v27, 0xffff0000, v27
	v_fmamk_f32 v36, v36, 0xbfb8aa3b, v72
	v_fmamk_f32 v38, v38, 0xbfb8aa3b, v68
	v_fmamk_f32 v24, v24, 0xbfb8aa3b, v73
	v_fmamk_f32 v26, v26, 0xbfb8aa3b, v69
	v_fmamk_f32 v37, v37, 0xbfb8aa3b, v74
	v_fmamk_f32 v39, v39, 0xbfb8aa3b, v70
	v_fmamk_f32 v25, v25, 0xbfb8aa3b, v75
	v_fmamk_f32 v27, v27, 0xbfb8aa3b, v71
	v_exp_f32_e32 v36, v36
	v_exp_f32_e32 v38, v38
	v_exp_f32_e32 v24, v24
	v_exp_f32_e32 v26, v26
	v_exp_f32_e32 v37, v37
	v_exp_f32_e32 v39, v39
	v_exp_f32_e32 v25, v25
	v_exp_f32_e32 v27, v27
	v_add_f32_e32 v36, 1.0, v36
	v_add_f32_e32 v38, 1.0, v38
	v_add_f32_e32 v24, 1.0, v24
	v_add_f32_e32 v26, 1.0, v26
	v_add_f32_e32 v37, 1.0, v37
	v_add_f32_e32 v39, 1.0, v39
	v_add_f32_e32 v25, 1.0, v25
	v_add_f32_e32 v27, 1.0, v27
	v_rcp_f32_e32 v36, v36
	v_rcp_f32_e32 v38, v38
	v_rcp_f32_e32 v24, v24
	v_rcp_f32_e32 v26, v26
	v_rcp_f32_e32 v37, v37
	v_rcp_f32_e32 v39, v39
	v_rcp_f32_e32 v25, v25
	v_rcp_f32_e32 v27, v27
	s_waitcnt vmcnt(2)
	v_lshlrev_b32_e32 v40, 16, v28
	v_and_b32_e32 v28, 0xffff0000, v28
	v_lshlrev_b32_e32 v41, 16, v29
	v_and_b32_e32 v29, 0xffff0000, v29
	v_lshlrev_b32_e32 v42, 16, v30
	v_and_b32_e32 v30, 0xffff0000, v30
	v_lshlrev_b32_e32 v43, 16, v31
	v_and_b32_e32 v31, 0xffff0000, v31
	v_fmac_f32_e32 v40, v16, v36
	v_fmac_f32_e32 v28, v17, v24
	v_fmac_f32_e32 v41, v18, v37
	v_fmac_f32_e32 v29, v19, v25
	v_fmac_f32_e32 v42, v12, v38
	v_fmac_f32_e32 v30, v13, v26
	v_fmac_f32_e32 v43, v14, v39
	v_fmac_f32_e32 v31, v15, v27
	v_cvt_pk_bf16_f32 v12, v40, v28
	v_cvt_pk_bf16_f32 v13, v41, v29
	v_cvt_pk_bf16_f32 v14, v42, v30
	v_cvt_pk_bf16_f32 v15, v43, v31
	global_store_dwordx4 v[82:83], v[12:15], off offset:256
	s_waitcnt vmcnt(2)
	v_lshlrev_b32_e32 v16, 16, v34
	v_and_b32_e32 v17, 0xffff0000, v34
	v_lshlrev_b32_e32 v12, 16, v32
	v_and_b32_e32 v13, 0xffff0000, v32
	v_lshlrev_b32_e32 v14, 16, v33
	v_and_b32_e32 v15, 0xffff0000, v33
	v_lshlrev_b32_e32 v18, 16, v35
	v_and_b32_e32 v19, 0xffff0000, v35
	v_fmamk_f32 v12, v12, 0xbfb8aa3b, v72
	v_fmamk_f32 v16, v16, 0xbfb8aa3b, v68
	v_fmamk_f32 v13, v13, 0xbfb8aa3b, v73
	v_fmamk_f32 v17, v17, 0xbfb8aa3b, v69
	v_fmamk_f32 v14, v14, 0xbfb8aa3b, v74
	v_fmamk_f32 v18, v18, 0xbfb8aa3b, v70
	v_fmamk_f32 v15, v15, 0xbfb8aa3b, v75
	v_fmamk_f32 v19, v19, 0xbfb8aa3b, v71
	v_exp_f32_e32 v12, v12
	v_exp_f32_e32 v16, v16
	v_exp_f32_e32 v13, v13
	v_exp_f32_e32 v17, v17
	v_exp_f32_e32 v14, v14
	v_exp_f32_e32 v18, v18
	v_exp_f32_e32 v15, v15
	v_exp_f32_e32 v19, v19
	v_add_f32_e32 v12, 1.0, v12
	v_add_f32_e32 v16, 1.0, v16
	v_add_f32_e32 v13, 1.0, v13
	v_add_f32_e32 v17, 1.0, v17
	v_add_f32_e32 v14, 1.0, v14
	v_add_f32_e32 v18, 1.0, v18
	v_add_f32_e32 v15, 1.0, v15
	v_add_f32_e32 v19, 1.0, v19
	v_rcp_f32_e32 v12, v12
	v_rcp_f32_e32 v16, v16
	v_rcp_f32_e32 v13, v13
	v_rcp_f32_e32 v17, v17
	v_rcp_f32_e32 v14, v14
	v_rcp_f32_e32 v18, v18
	v_rcp_f32_e32 v15, v15
	v_rcp_f32_e32 v19, v19
	s_waitcnt vmcnt(1)
	v_lshlrev_b32_e32 v24, 16, v20
	v_and_b32_e32 v20, 0xffff0000, v20
	v_lshlrev_b32_e32 v25, 16, v21
	v_and_b32_e32 v21, 0xffff0000, v21
	v_lshlrev_b32_e32 v26, 16, v22
	v_and_b32_e32 v22, 0xffff0000, v22
	v_lshlrev_b32_e32 v27, 16, v23
	v_and_b32_e32 v23, 0xffff0000, v23
	v_fmac_f32_e32 v24, v8, v12
	v_fmac_f32_e32 v20, v9, v13
	v_fmac_f32_e32 v25, v10, v14
	v_fmac_f32_e32 v21, v11, v15
	v_fmac_f32_e32 v26, v4, v16
	v_fmac_f32_e32 v22, v5, v17
	v_fmac_f32_e32 v27, v6, v18
	v_fmac_f32_e32 v23, v7, v19
	v_cvt_pk_bf16_f32 v4, v24, v20
	v_cvt_pk_bf16_f32 v5, v25, v21
	v_cvt_pk_bf16_f32 v6, v26, v22
	v_cvt_pk_bf16_f32 v7, v27, v23
	global_store_dwordx4 v[80:81], v[4:7], off offset:256
	s_cbranch_vccnz .LBB0_477
	s_andn2_b64 vcc, exec, s[36:37]
	s_cbranch_vccnz .LBB0_476
	s_barrier
	s_branch .LBB0_476
